# v53 with every second same-accumulator pair running k1 first (consecutive MFMAs across pair boundaries share the srcB register; per-accumulator sum of the two k-steps reassociated)
# baseline (speedup 1.0000x reference)
; #define PG8_STAGE(bufoff, gbase, voff) do { _Pragma("unroll") for (int _i = 0; _i < 2; ++_i) \
;         __builtin_amdgcn_global_load_lds((const unsigned*)((const char*)(gbase) + (voff)[_i]), (PG8_LAS unsigned*)(lds + (bufoff) + ldsw + _i * 8192), 16, 0, 0); } while (0)
; #define PG8_LDA(dst, b, h) do { _Pragma("unroll") for (int m = 0; m < 4; ++m) _Pragma("unroll") for (int k = 0; k < 2; ++k) dst[m][k] = *(const PG8_LAS bf16x8*)(lds + PG8_SA(b, h) + aoff + m * 2048 + k * 1024); } while (0)
; #define PG8_LDB(dst, b, h) do { _Pragma("unroll") for (int n = 0; n < 2; ++n) _Pragma("unroll") for (int k = 0; k < 2; ++k) dst[n][k] = *(const PG8_LAS bf16x8*)(lds + PG8_SB(b, h) + boff + n * 2048 + k * 1024); } while (0)
; #define PG8_MMA(ai, bj, At, Bt) do { __builtin_amdgcn_s_setprio(1); _Pragma("unroll") for (int m = 0; m < 4; ++m) _Pragma("unroll") for (int n = 0; n < 2; ++n) _Pragma("unroll") for (int k = 0; k < 2; ++k) \
;         acc[ai][bj][m][n] = __builtin_amdgcn_mfma_f32_16x16x32_bf16(Bt[n][k], At[m][k], acc[ai][bj][m][n], 0, 0, 0); __builtin_amdgcn_s_setprio(0); } while (0)
; #define PG8_BAR __builtin_amdgcn_s_barrier()
; template <class Epi, class Sched, bool ALIGN_EPI = false, bool SP2 = false>
; __device__ __forceinline__ void gemm_phase(PG8_LAS unsigned char* lds, const Gemm g, const Sched& S, const Epi& E) {
;     ...
;             const bool last = (t == nt - 2);
;             const char* a1 = cA + (size_t)(t + 1) * kstep;
;             const char* a2 = last ? nA : cA + (size_t)(t + 2) * kstep; const char* b2 = last ? nB : cB + (size_t)(t + 2) * kstep;
;             const char* a3 = a2 + kstep; const char* b3 = b2 + kstep;
;             if (last && has_next) S.a_ready(nxt);
;             if constexpr (Epi::MIDK) { if (t == (nt >> 1)) { E.midk(acc, wr, fr); asm volatile("s_waitcnt lgkmcnt(0)" ::: "memory"); } }
;             if constexpr (SP2) {
;             PG8_LDB(B0, 0, 0); PG8_LDB(B1, 0, 1); PG8_SCHED; PG8_LDA(At, 0, 0); PG8_STAGE(PG8_SA(1, 1), a1 + hstep, voffA);
;             PG8_WAIT_V(8); PG8_WAIT_L(0); PG8_BAR; PG8_MMA(0, 0, At, B0); PG8_MMA(0, 1, At, B1); PG8_BAR; PG8_SCHED;
;             PG8_LDA(At, 0, 1); PG8_STAGE(PG8_SB(0, 0), b2, voffB); PG8_STAGE(PG8_SB(0, 1), b2 + hstep, voffB); PG8_STAGE(PG8_SA(0, 0), a2, voffA);
;             PG8_WAIT_V(8); PG8_WAIT_L(0); PG8_BAR; PG8_MMA(1, 0, At, B0); PG8_MMA(1, 1, At, B1); PG8_BAR; PG8_SCHED;
.LBB0_349:
	ds_read_b128 v[150:153], v169
	ds_read_b128 v[154:157], v169 offset:1024
	ds_read_b128 v[158:161], v169 offset:2048
	ds_read_b128 v[162:165], v169 offset:3072
	ds_read_b128 v[174:177], v170
	ds_read_b128 v[178:181], v170 offset:1024
	ds_read_b128 v[182:185], v170 offset:2048
	ds_read_b128 v[186:189], v170 offset:3072
	s_add_u32 s0, s88, 0xfff00080
	s_addc_u32 s1, s89, -1
	s_cmp_eq_u32 s23, 60
	s_cselect_b32 s93, s51, s1
	s_cselect_b32 s92, s50, s0
	s_cselect_b32 s91, s53, s21
	s_cselect_b32 s90, s52, s9
	ds_read_b128 v[190:193], v171
	ds_read_b128 v[196:199], v171 offset:1024
	ds_read_b128 v[200:203], v171 offset:2048
	ds_read_b128 v[204:207], v171 offset:3072
	ds_read_b128 v[208:211], v171 offset:4096
	ds_read_b128 v[212:215], v171 offset:5120
	ds_read_b128 v[220:223], v171 offset:6144
	ds_read_b128 v[224:227], v171 offset:7168
	s_add_u32 s0, s88, 0xfff00000
	s_addc_u32 s1, s89, -1
	s_add_i32 m0, s27, 0x8000
	s_nop 0
	global_load_lds_dwordx4 v134, s[0:1]
	s_add_i32 m0, s27, 0xa000
	s_nop 0
	global_load_lds_dwordx4 v138, s[0:1]
	s_add_i32 m0, s27, 0xc000
	s_nop 0
	global_load_lds_dwordx4 v134, s[88:89]
	s_add_i32 m0, s27, 0xe000
	s_nop 0
	global_load_lds_dwordx4 v138, s[88:89]
	s_waitcnt lgkmcnt(0)
	s_setprio 1
	v_mfma_f32_16x16x32_bf16 v[38:41], v[150:153], v[190:193], v[38:41]
	v_mfma_f32_16x16x32_bf16 v[38:41], v[154:157], v[196:199], v[38:41]
	v_mfma_f32_16x16x32_bf16 v[30:33], v[162:165], v[196:199], v[30:33]
	v_mfma_f32_16x16x32_bf16 v[30:33], v[158:161], v[190:193], v[30:33]
	v_mfma_f32_16x16x32_bf16 v[50:53], v[174:177], v[190:193], v[50:53]
	v_mfma_f32_16x16x32_bf16 v[50:53], v[178:181], v[196:199], v[50:53]
	v_mfma_f32_16x16x32_bf16 v[46:49], v[186:189], v[196:199], v[46:49]
	v_mfma_f32_16x16x32_bf16 v[46:49], v[182:185], v[190:193], v[46:49]
	v_mfma_f32_16x16x32_bf16 v[130:133], v[150:153], v[200:203], v[130:133]
	v_mfma_f32_16x16x32_bf16 v[130:133], v[154:157], v[204:207], v[130:133]
	v_mfma_f32_16x16x32_bf16 v[126:129], v[162:165], v[204:207], v[126:129]
	v_mfma_f32_16x16x32_bf16 v[126:129], v[158:161], v[200:203], v[126:129]
	v_mfma_f32_16x16x32_bf16 v[122:125], v[174:177], v[200:203], v[122:125]
	v_mfma_f32_16x16x32_bf16 v[122:125], v[178:181], v[204:207], v[122:125]
	v_mfma_f32_16x16x32_bf16 v[118:121], v[186:189], v[204:207], v[118:121]
	v_mfma_f32_16x16x32_bf16 v[118:121], v[182:185], v[200:203], v[118:121]
	v_mfma_f32_16x16x32_bf16 v[114:117], v[150:153], v[208:211], v[114:117]
	v_mfma_f32_16x16x32_bf16 v[114:117], v[154:157], v[212:215], v[114:117]
	v_mfma_f32_16x16x32_bf16 v[110:113], v[162:165], v[212:215], v[110:113]
	v_mfma_f32_16x16x32_bf16 v[110:113], v[158:161], v[208:211], v[110:113]
	v_mfma_f32_16x16x32_bf16 v[106:109], v[174:177], v[208:211], v[106:109]
	v_mfma_f32_16x16x32_bf16 v[106:109], v[178:181], v[212:215], v[106:109]
	v_mfma_f32_16x16x32_bf16 v[102:105], v[186:189], v[212:215], v[102:105]
	v_mfma_f32_16x16x32_bf16 v[102:105], v[182:185], v[208:211], v[102:105]
	v_mfma_f32_16x16x32_bf16 v[98:101], v[150:153], v[220:223], v[98:101]
	v_mfma_f32_16x16x32_bf16 v[98:101], v[154:157], v[224:227], v[98:101]
	v_mfma_f32_16x16x32_bf16 v[94:97], v[162:165], v[224:227], v[94:97]
	v_mfma_f32_16x16x32_bf16 v[94:97], v[158:161], v[220:223], v[94:97]
	v_mfma_f32_16x16x32_bf16 v[90:93], v[174:177], v[220:223], v[90:93]
	v_mfma_f32_16x16x32_bf16 v[90:93], v[178:181], v[224:227], v[90:93]
	v_mfma_f32_16x16x32_bf16 v[86:89], v[186:189], v[224:227], v[86:89]
	v_mfma_f32_16x16x32_bf16 v[86:89], v[182:185], v[220:223], v[86:89]
	s_setprio 0
	s_waitcnt vmcnt(8)
	s_barrier
	ds_read_b128 v[190:193], v171 offset:16384
	ds_read_b128 v[196:199], v171 offset:17408
	ds_read_b128 v[200:203], v171 offset:18432
	ds_read_b128 v[204:207], v171 offset:19456
	ds_read_b128 v[208:211], v171 offset:20480
	ds_read_b128 v[212:215], v171 offset:21504
	ds_read_b128 v[220:223], v171 offset:22528
	ds_read_b128 v[224:227], v171 offset:23552
	s_add_u32 vcc_lo, s90, 0x100000
	s_addc_u32 vcc_hi, s91, 0
	s_add_i32 m0, s27, 0x10000
	s_nop 0
	global_load_lds_dwordx4 v136, s[90:91]
	s_add_i32 m0, s27, 0x12000
	s_nop 0
	global_load_lds_dwordx4 v140, s[90:91]
	s_add_i32 m0, s27, 0x14000
	s_nop 0
	global_load_lds_dwordx4 v136, vcc
	s_add_i32 m0, s27, 0x16000
	s_nop 0
	global_load_lds_dwordx4 v140, vcc
	s_waitcnt lgkmcnt(0)
	s_setprio 1
	v_mfma_f32_16x16x32_bf16 v[82:85], v[150:153], v[190:193], v[82:85]
	v_mfma_f32_16x16x32_bf16 v[82:85], v[154:157], v[196:199], v[82:85]
	v_mfma_f32_16x16x32_bf16 v[78:81], v[162:165], v[196:199], v[78:81]
	v_mfma_f32_16x16x32_bf16 v[78:81], v[158:161], v[190:193], v[78:81]
	v_mfma_f32_16x16x32_bf16 v[74:77], v[174:177], v[190:193], v[74:77]
	v_mfma_f32_16x16x32_bf16 v[74:77], v[178:181], v[196:199], v[74:77]
	v_mfma_f32_16x16x32_bf16 v[70:73], v[186:189], v[196:199], v[70:73]
	v_mfma_f32_16x16x32_bf16 v[70:73], v[182:185], v[190:193], v[70:73]
	v_mfma_f32_16x16x32_bf16 v[66:69], v[150:153], v[200:203], v[66:69]
	v_mfma_f32_16x16x32_bf16 v[66:69], v[154:157], v[204:207], v[66:69]
	v_mfma_f32_16x16x32_bf16 v[62:65], v[162:165], v[204:207], v[62:65]
	v_mfma_f32_16x16x32_bf16 v[62:65], v[158:161], v[200:203], v[62:65]
	v_mfma_f32_16x16x32_bf16 v[58:61], v[174:177], v[200:203], v[58:61]
	v_mfma_f32_16x16x32_bf16 v[58:61], v[178:181], v[204:207], v[58:61]
	v_mfma_f32_16x16x32_bf16 v[54:57], v[186:189], v[204:207], v[54:57]
	v_mfma_f32_16x16x32_bf16 v[54:57], v[182:185], v[200:203], v[54:57]
	v_mfma_f32_16x16x32_bf16 v[42:45], v[150:153], v[208:211], v[42:45]
	v_mfma_f32_16x16x32_bf16 v[42:45], v[154:157], v[212:215], v[42:45]
	v_mfma_f32_16x16x32_bf16 v[34:37], v[162:165], v[212:215], v[34:37]
	v_mfma_f32_16x16x32_bf16 v[34:37], v[158:161], v[208:211], v[34:37]
	v_mfma_f32_16x16x32_bf16 v[26:29], v[174:177], v[208:211], v[26:29]
	v_mfma_f32_16x16x32_bf16 v[26:29], v[178:181], v[212:215], v[26:29]
	v_mfma_f32_16x16x32_bf16 v[22:25], v[186:189], v[212:215], v[22:25]
	v_mfma_f32_16x16x32_bf16 v[22:25], v[182:185], v[208:211], v[22:25]
	v_mfma_f32_16x16x32_bf16 v[18:21], v[150:153], v[220:223], v[18:21]
	v_mfma_f32_16x16x32_bf16 v[18:21], v[154:157], v[224:227], v[18:21]
	v_mfma_f32_16x16x32_bf16 v[14:17], v[162:165], v[224:227], v[14:17]
	v_mfma_f32_16x16x32_bf16 v[14:17], v[158:161], v[220:223], v[14:17]
	v_mfma_f32_16x16x32_bf16 v[10:13], v[174:177], v[220:223], v[10:13]
	v_mfma_f32_16x16x32_bf16 v[10:13], v[178:181], v[224:227], v[10:13]
	v_mfma_f32_16x16x32_bf16 v[4:7], v[182:185], v[220:223], v[6:9]
	v_mfma_f32_16x16x32_bf16 v[4:7], v[186:189], v[224:227], v[4:7]
	s_setprio 0
	s_waitcnt vmcnt(6)
	s_barrier
; #define PG8_STAGE(bufoff, gbase, voff) do { _Pragma("unroll") for (int _i = 0; _i < 2; ++_i) \
;         __builtin_amdgcn_global_load_lds((const unsigned*)((const char*)(gbase) + (voff)[_i]), (PG8_LAS unsigned*)(lds + (bufoff) + ldsw + _i * 8192), 16, 0, 0); } while (0)
; #define PG8_LDA(dst, b, h) do { _Pragma("unroll") for (int m = 0; m < 4; ++m) _Pragma("unroll") for (int k = 0; k < 2; ++k) dst[m][k] = *(const PG8_LAS bf16x8*)(lds + PG8_SA(b, h) + aoff + m * 2048 + k * 1024); } while (0)
; #define PG8_LDB(dst, b, h) do { _Pragma("unroll") for (int n = 0; n < 2; ++n) _Pragma("unroll") for (int k = 0; k < 2; ++k) dst[n][k] = *(const PG8_LAS bf16x8*)(lds + PG8_SB(b, h) + boff + n * 2048 + k * 1024); } while (0)
; #define PG8_MMA(ai, bj, At, Bt) do { __builtin_amdgcn_s_setprio(1); _Pragma("unroll") for (int m = 0; m < 4; ++m) _Pragma("unroll") for (int n = 0; n < 2; ++n) _Pragma("unroll") for (int k = 0; k < 2; ++k) \
;         acc[ai][bj][m][n] = __builtin_amdgcn_mfma_f32_16x16x32_bf16(Bt[n][k], At[m][k], acc[ai][bj][m][n], 0, 0, 0); __builtin_amdgcn_s_setprio(0); } while (0)
; #define PG8_WAIT_V(n) asm volatile("s_waitcnt vmcnt(" #n ")" ::: "memory")
; #define PG8_WAIT_L(n) asm volatile("s_waitcnt lgkmcnt(" #n ")" ::: "memory")
; #define PG8_BAR __builtin_amdgcn_s_barrier()
; #define PG8_SCHED __builtin_amdgcn_sched_barrier(0)
; template <class Epi, class Sched, bool ALIGN_EPI = false, bool SP2 = false>
; __device__ __forceinline__ void gemm_phase(PG8_LAS unsigned char* lds, const Gemm g, const Sched& S, const Epi& E) {
;     ...
;             PG8_LDB(B0, 1, 0); PG8_LDB(B1, 1, 1); PG8_SCHED; PG8_LDA(At, 1, 0); PG8_STAGE(PG8_SA(0, 1), a2 + hstep, voffA);
;             PG8_WAIT_V(8); PG8_WAIT_L(0); PG8_BAR; PG8_MMA(0, 0, At, B0); PG8_MMA(0, 1, At, B1); PG8_BAR; PG8_SCHED;
;             PG8_LDA(At, 1, 1); PG8_STAGE(PG8_SB(1, 0), b3, voffB); PG8_STAGE(PG8_SB(1, 1), b3 + hstep, voffB); PG8_STAGE(PG8_SA(1, 0), a3, voffA);
;             PG8_WAIT_V(8); PG8_WAIT_L(0); PG8_BAR; PG8_MMA(1, 0, At, B0); PG8_MMA(1, 1, At, B1); PG8_BAR; PG8_SCHED;
	s_add_i32 s0, 0, 0x18000
	v_add_u32_e32 v3, s0, v167
	s_add_i32 s1, 0, 0x1c000
	ds_read_b128 v[150:153], v3
	ds_read_b128 v[154:157], v3 offset:1024
	ds_read_b128 v[158:161], v3 offset:2048
	ds_read_b128 v[162:165], v3 offset:3072
	v_add_u32_e32 v3, s1, v167
	ds_read_b128 v[174:177], v3
	ds_read_b128 v[178:181], v3 offset:1024
	ds_read_b128 v[182:185], v3 offset:2048
	ds_read_b128 v[186:189], v3 offset:3072
	ds_read_b128 v[190:193], v171 offset:32768
	ds_read_b128 v[196:199], v171 offset:33792
	ds_read_b128 v[200:203], v171 offset:34816
	ds_read_b128 v[204:207], v171 offset:35840
	ds_read_b128 v[208:211], v171 offset:36864
	ds_read_b128 v[212:215], v171 offset:37888
	ds_read_b128 v[220:223], v171 offset:38912
	ds_read_b128 v[224:227], v171 offset:39936
	s_add_u32 vcc_lo, s92, 0x100000
	s_addc_u32 vcc_hi, s93, 0
	s_mov_b32 m0, s27
	s_nop 0
	global_load_lds_dwordx4 v134, s[92:93]
	s_add_i32 m0, s27, 0x2000
	s_nop 0
	global_load_lds_dwordx4 v138, s[92:93]
	s_add_i32 m0, s27, 0x4000
	s_nop 0
	global_load_lds_dwordx4 v134, vcc
	s_add_i32 m0, s27, 0x6000
	s_nop 0
	global_load_lds_dwordx4 v138, vcc
	s_waitcnt lgkmcnt(0)
	s_setprio 1
	v_mfma_f32_16x16x32_bf16 v[38:41], v[150:153], v[190:193], v[38:41]
	v_mfma_f32_16x16x32_bf16 v[38:41], v[154:157], v[196:199], v[38:41]
	v_mfma_f32_16x16x32_bf16 v[30:33], v[162:165], v[196:199], v[30:33]
	v_mfma_f32_16x16x32_bf16 v[30:33], v[158:161], v[190:193], v[30:33]
	v_mfma_f32_16x16x32_bf16 v[50:53], v[174:177], v[190:193], v[50:53]
	v_mfma_f32_16x16x32_bf16 v[50:53], v[178:181], v[196:199], v[50:53]
	v_mfma_f32_16x16x32_bf16 v[46:49], v[186:189], v[196:199], v[46:49]
	v_mfma_f32_16x16x32_bf16 v[46:49], v[182:185], v[190:193], v[46:49]
	v_mfma_f32_16x16x32_bf16 v[130:133], v[150:153], v[200:203], v[130:133]
	v_mfma_f32_16x16x32_bf16 v[130:133], v[154:157], v[204:207], v[130:133]
	v_mfma_f32_16x16x32_bf16 v[126:129], v[162:165], v[204:207], v[126:129]
	v_mfma_f32_16x16x32_bf16 v[126:129], v[158:161], v[200:203], v[126:129]
	v_mfma_f32_16x16x32_bf16 v[122:125], v[174:177], v[200:203], v[122:125]
	v_mfma_f32_16x16x32_bf16 v[122:125], v[178:181], v[204:207], v[122:125]
	v_mfma_f32_16x16x32_bf16 v[118:121], v[186:189], v[204:207], v[118:121]
	v_mfma_f32_16x16x32_bf16 v[118:121], v[182:185], v[200:203], v[118:121]
	v_mfma_f32_16x16x32_bf16 v[114:117], v[150:153], v[208:211], v[114:117]
	v_mfma_f32_16x16x32_bf16 v[114:117], v[154:157], v[212:215], v[114:117]
	v_mfma_f32_16x16x32_bf16 v[110:113], v[162:165], v[212:215], v[110:113]
	v_mfma_f32_16x16x32_bf16 v[110:113], v[158:161], v[208:211], v[110:113]
	v_mfma_f32_16x16x32_bf16 v[106:109], v[174:177], v[208:211], v[106:109]
	v_mfma_f32_16x16x32_bf16 v[106:109], v[178:181], v[212:215], v[106:109]
	v_mfma_f32_16x16x32_bf16 v[102:105], v[186:189], v[212:215], v[102:105]
	v_mfma_f32_16x16x32_bf16 v[102:105], v[182:185], v[208:211], v[102:105]
	v_mfma_f32_16x16x32_bf16 v[98:101], v[150:153], v[220:223], v[98:101]
	v_mfma_f32_16x16x32_bf16 v[98:101], v[154:157], v[224:227], v[98:101]
	v_mfma_f32_16x16x32_bf16 v[94:97], v[162:165], v[224:227], v[94:97]
	v_mfma_f32_16x16x32_bf16 v[94:97], v[158:161], v[220:223], v[94:97]
	v_mfma_f32_16x16x32_bf16 v[90:93], v[174:177], v[220:223], v[90:93]
	v_mfma_f32_16x16x32_bf16 v[90:93], v[178:181], v[224:227], v[90:93]
	v_mfma_f32_16x16x32_bf16 v[86:89], v[186:189], v[224:227], v[86:89]
	v_mfma_f32_16x16x32_bf16 v[86:89], v[182:185], v[220:223], v[86:89]
	s_setprio 0
	s_waitcnt vmcnt(8)
	s_barrier
	ds_read_b128 v[190:193], v171 offset:49152
	ds_read_b128 v[196:199], v171 offset:50176
	ds_read_b128 v[200:203], v171 offset:51200
	ds_read_b128 v[204:207], v171 offset:52224
	ds_read_b128 v[208:211], v171 offset:53248
	ds_read_b128 v[212:215], v171 offset:54272
	ds_read_b128 v[220:223], v171 offset:55296
	ds_read_b128 v[224:227], v171 offset:56320
	s_add_u32 s0, s90, 0x80
	s_addc_u32 s1, s91, 0
	s_add_u32 vcc_lo, s0, 0x100000
	s_addc_u32 vcc_hi, s1, 0
	s_add_i32 m0, s27, 0x18000
	s_nop 0
	global_load_lds_dwordx4 v136, s[0:1]
	s_add_i32 m0, s27, 0x1a000
	s_nop 0
	global_load_lds_dwordx4 v140, s[0:1]
	s_add_i32 m0, s27, 0x1c000
	s_nop 0
	global_load_lds_dwordx4 v136, vcc
	s_add_i32 m0, s27, 0x1e000
	s_nop 0
	global_load_lds_dwordx4 v140, vcc
	s_waitcnt lgkmcnt(0)
	s_setprio 1
	v_mfma_f32_16x16x32_bf16 v[82:85], v[150:153], v[190:193], v[82:85]
	v_mfma_f32_16x16x32_bf16 v[82:85], v[154:157], v[196:199], v[82:85]
	v_mfma_f32_16x16x32_bf16 v[78:81], v[162:165], v[196:199], v[78:81]
	v_mfma_f32_16x16x32_bf16 v[78:81], v[158:161], v[190:193], v[78:81]
	v_mfma_f32_16x16x32_bf16 v[74:77], v[174:177], v[190:193], v[74:77]
	v_mfma_f32_16x16x32_bf16 v[74:77], v[178:181], v[196:199], v[74:77]
	v_mfma_f32_16x16x32_bf16 v[70:73], v[186:189], v[196:199], v[70:73]
	v_mfma_f32_16x16x32_bf16 v[70:73], v[182:185], v[190:193], v[70:73]
	v_mfma_f32_16x16x32_bf16 v[66:69], v[150:153], v[200:203], v[66:69]
	v_mfma_f32_16x16x32_bf16 v[66:69], v[154:157], v[204:207], v[66:69]
	v_mfma_f32_16x16x32_bf16 v[62:65], v[162:165], v[204:207], v[62:65]
	v_mfma_f32_16x16x32_bf16 v[62:65], v[158:161], v[200:203], v[62:65]
	v_mfma_f32_16x16x32_bf16 v[58:61], v[174:177], v[200:203], v[58:61]
	v_mfma_f32_16x16x32_bf16 v[58:61], v[178:181], v[204:207], v[58:61]
	v_mfma_f32_16x16x32_bf16 v[54:57], v[186:189], v[204:207], v[54:57]
	v_mfma_f32_16x16x32_bf16 v[54:57], v[182:185], v[200:203], v[54:57]
	v_mfma_f32_16x16x32_bf16 v[42:45], v[150:153], v[208:211], v[42:45]
	v_mfma_f32_16x16x32_bf16 v[42:45], v[154:157], v[212:215], v[42:45]
	v_mfma_f32_16x16x32_bf16 v[34:37], v[162:165], v[212:215], v[34:37]
	v_mfma_f32_16x16x32_bf16 v[34:37], v[158:161], v[208:211], v[34:37]
	v_mfma_f32_16x16x32_bf16 v[26:29], v[174:177], v[208:211], v[26:29]
	v_mfma_f32_16x16x32_bf16 v[26:29], v[178:181], v[212:215], v[26:29]
	v_mfma_f32_16x16x32_bf16 v[22:25], v[186:189], v[212:215], v[22:25]
	v_mfma_f32_16x16x32_bf16 v[22:25], v[182:185], v[208:211], v[22:25]
	v_mfma_f32_16x16x32_bf16 v[18:21], v[150:153], v[220:223], v[18:21]
	v_mfma_f32_16x16x32_bf16 v[18:21], v[154:157], v[224:227], v[18:21]
	v_mfma_f32_16x16x32_bf16 v[14:17], v[162:165], v[224:227], v[14:17]
	v_mfma_f32_16x16x32_bf16 v[14:17], v[158:161], v[220:223], v[14:17]
	v_mfma_f32_16x16x32_bf16 v[8:11], v[174:177], v[220:223], v[10:13]
	v_mfma_f32_16x16x32_bf16 v[10:13], v[178:181], v[224:227], v[8:11]
	v_mfma_f32_16x16x32_bf16 v[4:7], v[182:185], v[220:223], v[4:7]
	v_mfma_f32_16x16x32_bf16 v[6:9], v[186:189], v[224:227], v[4:7]
	s_setprio 0
	s_waitcnt vmcnt(6)
	s_barrier
	s_add_i32 s23, s23, 2
	s_add_u32 s88, s88, 0x100
	s_addc_u32 s89, s89, 0
	s_add_u32 s9, s9, 0x100
	s_addc_u32 s21, s21, 0
	s_cmp_gt_u32 s23, 61
	s_cbranch_scc0 .LBB0_349
	s_branch .Lip_exit
; #define PG8_STAGE(bufoff, gbase, voff) do { _Pragma("unroll") for (int _i = 0; _i < 2; ++_i) \
;         __builtin_amdgcn_global_load_lds((const unsigned*)((const char*)(gbase) + (voff)[_i]), (PG8_LAS unsigned*)(lds + (bufoff) + ldsw + _i * 8192), 16, 0, 0); } while (0)
; #define PG8_LDA(dst, b, h) do { _Pragma("unroll") for (int m = 0; m < 4; ++m) _Pragma("unroll") for (int k = 0; k < 2; ++k) dst[m][k] = *(const PG8_LAS bf16x8*)(lds + PG8_SA(b, h) + aoff + m * 2048 + k * 1024); } while (0)
; #define PG8_LDB(dst, b, h) do { _Pragma("unroll") for (int n = 0; n < 2; ++n) _Pragma("unroll") for (int k = 0; k < 2; ++k) dst[n][k] = *(const PG8_LAS bf16x8*)(lds + PG8_SB(b, h) + boff + n * 2048 + k * 1024); } while (0)
; #define PG8_MMA(ai, bj, At, Bt) do { __builtin_amdgcn_s_setprio(1); _Pragma("unroll") for (int m = 0; m < 4; ++m) _Pragma("unroll") for (int n = 0; n < 2; ++n) _Pragma("unroll") for (int k = 0; k < 2; ++k) \
;         acc[ai][bj][m][n] = __builtin_amdgcn_mfma_f32_16x16x32_bf16(Bt[n][k], At[m][k], acc[ai][bj][m][n], 0, 0, 0); __builtin_amdgcn_s_setprio(0); } while (0)
; #define PG8_WAIT_V(n) asm volatile("s_waitcnt vmcnt(" #n ")" ::: "memory")
; #define PG8_WAIT_L(n) asm volatile("s_waitcnt lgkmcnt(" #n ")" ::: "memory")
; #define PG8_BAR __builtin_amdgcn_s_barrier()
; #define PG8_SCHED __builtin_amdgcn_sched_barrier(0)
; template <class Epi, class Sched, bool ALIGN_EPI = false, bool SP2 = false>
; __device__ __forceinline__ void gemm_phase(PG8_LAS unsigned char* lds, const Gemm g, const Sched& S, const Epi& E) {
;     ...
;             PG8_LDB(B0, 0, 0); PG8_LDB(B1, 0, 1); PG8_SCHED; PG8_LDA(At, 0, 0); PG8_STAGE(PG8_SA(1, 1), a1 + hstep, voffA);
;             PG8_WAIT_V(8); PG8_WAIT_L(0); PG8_BAR; PG8_MMA(0, 0, At, B0); PG8_MMA(0, 1, At, B1); PG8_BAR; PG8_SCHED;
;             PG8_LDA(At, 0, 1); PG8_STAGE(PG8_SB(0, 0), b2, voffB); PG8_STAGE(PG8_SB(0, 1), b2 + hstep, voffB); PG8_STAGE(PG8_SA(0, 0), a2, voffA);
;             PG8_WAIT_V(8); PG8_WAIT_L(0); PG8_BAR; PG8_MMA(1, 0, At, B0); PG8_MMA(1, 1, At, B1); PG8_BAR; PG8_SCHED;
.Lip_h1:
	ds_read_b128 v[150:153], v169
	ds_read_b128 v[154:157], v169 offset:1024
	ds_read_b128 v[158:161], v169 offset:2048
	ds_read_b128 v[162:165], v169 offset:3072
	ds_read_b128 v[174:177], v170
	ds_read_b128 v[178:181], v170 offset:1024
	ds_read_b128 v[182:185], v170 offset:2048
	ds_read_b128 v[186:189], v170 offset:3072
	s_add_u32 s0, s88, 0xfff00080
	s_addc_u32 s1, s89, -1
	s_cmp_eq_u32 s23, 60
	s_cselect_b32 s93, s51, s1
	s_cselect_b32 s92, s50, s0
	s_cselect_b32 s91, s53, s21
	s_cselect_b32 s90, s52, s9
	ds_read_b128 v[190:193], v171
	ds_read_b128 v[196:199], v171 offset:1024
	ds_read_b128 v[200:203], v171 offset:2048
	ds_read_b128 v[204:207], v171 offset:3072
	ds_read_b128 v[208:211], v171 offset:4096
	ds_read_b128 v[212:215], v171 offset:5120
	ds_read_b128 v[220:223], v171 offset:6144
	ds_read_b128 v[224:227], v171 offset:7168
	s_add_u32 s0, s88, 0xfff00000
	s_addc_u32 s1, s89, -1
	s_add_i32 m0, s27, 0x8000
	s_nop 0
	global_load_lds_dwordx4 v134, s[0:1]
	s_add_i32 m0, s27, 0xa000
	s_nop 0
	global_load_lds_dwordx4 v138, s[0:1]
	s_add_i32 m0, s27, 0xc000
	s_nop 0
	global_load_lds_dwordx4 v134, s[88:89]
	s_add_i32 m0, s27, 0xe000
	s_nop 0
	global_load_lds_dwordx4 v138, s[88:89]
	s_sleep 2
	s_waitcnt lgkmcnt(0)
	s_waitcnt vmcnt(8)
	s_barrier
	s_setprio 2
	v_mfma_f32_16x16x32_bf16 v[38:41], v[150:153], v[190:193], v[38:41]
	v_mfma_f32_16x16x32_bf16 v[38:41], v[154:157], v[196:199], v[38:41]
	v_mfma_f32_16x16x32_bf16 v[30:33], v[162:165], v[196:199], v[30:33]
	v_mfma_f32_16x16x32_bf16 v[30:33], v[158:161], v[190:193], v[30:33]
	v_mfma_f32_16x16x32_bf16 v[50:53], v[174:177], v[190:193], v[50:53]
	v_mfma_f32_16x16x32_bf16 v[50:53], v[178:181], v[196:199], v[50:53]
	v_mfma_f32_16x16x32_bf16 v[46:49], v[186:189], v[196:199], v[46:49]
	v_mfma_f32_16x16x32_bf16 v[46:49], v[182:185], v[190:193], v[46:49]
	v_mfma_f32_16x16x32_bf16 v[130:133], v[150:153], v[200:203], v[130:133]
	v_mfma_f32_16x16x32_bf16 v[130:133], v[154:157], v[204:207], v[130:133]
	v_mfma_f32_16x16x32_bf16 v[126:129], v[162:165], v[204:207], v[126:129]
	v_mfma_f32_16x16x32_bf16 v[126:129], v[158:161], v[200:203], v[126:129]
	v_mfma_f32_16x16x32_bf16 v[122:125], v[174:177], v[200:203], v[122:125]
	v_mfma_f32_16x16x32_bf16 v[122:125], v[178:181], v[204:207], v[122:125]
	v_mfma_f32_16x16x32_bf16 v[118:121], v[186:189], v[204:207], v[118:121]
	v_mfma_f32_16x16x32_bf16 v[118:121], v[182:185], v[200:203], v[118:121]
	v_mfma_f32_16x16x32_bf16 v[114:117], v[150:153], v[208:211], v[114:117]
	v_mfma_f32_16x16x32_bf16 v[114:117], v[154:157], v[212:215], v[114:117]
	v_mfma_f32_16x16x32_bf16 v[110:113], v[162:165], v[212:215], v[110:113]
	v_mfma_f32_16x16x32_bf16 v[110:113], v[158:161], v[208:211], v[110:113]
	v_mfma_f32_16x16x32_bf16 v[106:109], v[174:177], v[208:211], v[106:109]
	v_mfma_f32_16x16x32_bf16 v[106:109], v[178:181], v[212:215], v[106:109]
	v_mfma_f32_16x16x32_bf16 v[102:105], v[186:189], v[212:215], v[102:105]
	v_mfma_f32_16x16x32_bf16 v[102:105], v[182:185], v[208:211], v[102:105]
	v_mfma_f32_16x16x32_bf16 v[98:101], v[150:153], v[220:223], v[98:101]
	v_mfma_f32_16x16x32_bf16 v[98:101], v[154:157], v[224:227], v[98:101]
	v_mfma_f32_16x16x32_bf16 v[94:97], v[162:165], v[224:227], v[94:97]
	v_mfma_f32_16x16x32_bf16 v[94:97], v[158:161], v[220:223], v[94:97]
	v_mfma_f32_16x16x32_bf16 v[90:93], v[174:177], v[220:223], v[90:93]
	v_mfma_f32_16x16x32_bf16 v[90:93], v[178:181], v[224:227], v[90:93]
	v_mfma_f32_16x16x32_bf16 v[86:89], v[186:189], v[224:227], v[86:89]
	v_mfma_f32_16x16x32_bf16 v[86:89], v[182:185], v[220:223], v[86:89]
	s_setprio 0
	ds_read_b128 v[190:193], v171 offset:16384
	ds_read_b128 v[196:199], v171 offset:17408
	ds_read_b128 v[200:203], v171 offset:18432
	ds_read_b128 v[204:207], v171 offset:19456
	ds_read_b128 v[208:211], v171 offset:20480
	ds_read_b128 v[212:215], v171 offset:21504
	ds_read_b128 v[220:223], v171 offset:22528
	ds_read_b128 v[224:227], v171 offset:23552
	s_add_u32 vcc_lo, s90, 0x100000
	s_addc_u32 vcc_hi, s91, 0
	s_add_i32 m0, s27, 0x10000
	s_nop 0
	global_load_lds_dwordx4 v136, s[90:91]
	s_add_i32 m0, s27, 0x12000
	s_nop 0
	global_load_lds_dwordx4 v140, s[90:91]
	s_add_i32 m0, s27, 0x14000
	s_nop 0
	global_load_lds_dwordx4 v136, vcc
	s_add_i32 m0, s27, 0x16000
	s_nop 0
	global_load_lds_dwordx4 v140, vcc
	s_sleep 2
	s_waitcnt lgkmcnt(0)
	s_waitcnt vmcnt(6)
	s_barrier
; #define PG8_STAGE(bufoff, gbase, voff) do { _Pragma("unroll") for (int _i = 0; _i < 2; ++_i) \
;         __builtin_amdgcn_global_load_lds((const unsigned*)((const char*)(gbase) + (voff)[_i]), (PG8_LAS unsigned*)(lds + (bufoff) + ldsw + _i * 8192), 16, 0, 0); } while (0)
; #define PG8_LDA(dst, b, h) do { _Pragma("unroll") for (int m = 0; m < 4; ++m) _Pragma("unroll") for (int k = 0; k < 2; ++k) dst[m][k] = *(const PG8_LAS bf16x8*)(lds + PG8_SA(b, h) + aoff + m * 2048 + k * 1024); } while (0)
; #define PG8_LDB(dst, b, h) do { _Pragma("unroll") for (int n = 0; n < 2; ++n) _Pragma("unroll") for (int k = 0; k < 2; ++k) dst[n][k] = *(const PG8_LAS bf16x8*)(lds + PG8_SB(b, h) + boff + n * 2048 + k * 1024); } while (0)
; #define PG8_MMA(ai, bj, At, Bt) do { __builtin_amdgcn_s_setprio(1); _Pragma("unroll") for (int m = 0; m < 4; ++m) _Pragma("unroll") for (int n = 0; n < 2; ++n) _Pragma("unroll") for (int k = 0; k < 2; ++k) \
;         acc[ai][bj][m][n] = __builtin_amdgcn_mfma_f32_16x16x32_bf16(Bt[n][k], At[m][k], acc[ai][bj][m][n], 0, 0, 0); __builtin_amdgcn_s_setprio(0); } while (0)
; #define PG8_WAIT_V(n) asm volatile("s_waitcnt vmcnt(" #n ")" ::: "memory")
; #define PG8_WAIT_L(n) asm volatile("s_waitcnt lgkmcnt(" #n ")" ::: "memory")
; #define PG8_BAR __builtin_amdgcn_s_barrier()
; #define PG8_SCHED __builtin_amdgcn_sched_barrier(0)
; template <class Epi, class Sched, bool ALIGN_EPI = false, bool SP2 = false>
; __device__ __forceinline__ void gemm_phase(PG8_LAS unsigned char* lds, const Gemm g, const Sched& S, const Epi& E) {
;     ...
;             PG8_WAIT_V(8); PG8_WAIT_L(0); PG8_BAR; PG8_MMA(1, 0, At, B0); PG8_MMA(1, 1, At, B1); PG8_BAR; PG8_SCHED;
;             PG8_LDB(B0, 1, 0); PG8_LDB(B1, 1, 1); PG8_SCHED; PG8_LDA(At, 1, 0); PG8_STAGE(PG8_SA(0, 1), a2 + hstep, voffA);
;             PG8_WAIT_V(8); PG8_WAIT_L(0); PG8_BAR; PG8_MMA(0, 0, At, B0); PG8_MMA(0, 1, At, B1); PG8_BAR; PG8_SCHED;
	s_setprio 2
	v_mfma_f32_16x16x32_bf16 v[82:85], v[150:153], v[190:193], v[82:85]
	v_mfma_f32_16x16x32_bf16 v[82:85], v[154:157], v[196:199], v[82:85]
	v_mfma_f32_16x16x32_bf16 v[78:81], v[162:165], v[196:199], v[78:81]
	v_mfma_f32_16x16x32_bf16 v[78:81], v[158:161], v[190:193], v[78:81]
	v_mfma_f32_16x16x32_bf16 v[74:77], v[174:177], v[190:193], v[74:77]
	v_mfma_f32_16x16x32_bf16 v[74:77], v[178:181], v[196:199], v[74:77]
	v_mfma_f32_16x16x32_bf16 v[70:73], v[186:189], v[196:199], v[70:73]
	v_mfma_f32_16x16x32_bf16 v[70:73], v[182:185], v[190:193], v[70:73]
	v_mfma_f32_16x16x32_bf16 v[66:69], v[150:153], v[200:203], v[66:69]
	v_mfma_f32_16x16x32_bf16 v[66:69], v[154:157], v[204:207], v[66:69]
	v_mfma_f32_16x16x32_bf16 v[62:65], v[162:165], v[204:207], v[62:65]
	v_mfma_f32_16x16x32_bf16 v[62:65], v[158:161], v[200:203], v[62:65]
	v_mfma_f32_16x16x32_bf16 v[58:61], v[174:177], v[200:203], v[58:61]
	v_mfma_f32_16x16x32_bf16 v[58:61], v[178:181], v[204:207], v[58:61]
	v_mfma_f32_16x16x32_bf16 v[54:57], v[186:189], v[204:207], v[54:57]
	v_mfma_f32_16x16x32_bf16 v[54:57], v[182:185], v[200:203], v[54:57]
	v_mfma_f32_16x16x32_bf16 v[42:45], v[150:153], v[208:211], v[42:45]
	v_mfma_f32_16x16x32_bf16 v[42:45], v[154:157], v[212:215], v[42:45]
	v_mfma_f32_16x16x32_bf16 v[34:37], v[162:165], v[212:215], v[34:37]
	v_mfma_f32_16x16x32_bf16 v[34:37], v[158:161], v[208:211], v[34:37]
	v_mfma_f32_16x16x32_bf16 v[26:29], v[174:177], v[208:211], v[26:29]
	v_mfma_f32_16x16x32_bf16 v[26:29], v[178:181], v[212:215], v[26:29]
	v_mfma_f32_16x16x32_bf16 v[22:25], v[186:189], v[212:215], v[22:25]
	v_mfma_f32_16x16x32_bf16 v[22:25], v[182:185], v[208:211], v[22:25]
	v_mfma_f32_16x16x32_bf16 v[18:21], v[150:153], v[220:223], v[18:21]
	v_mfma_f32_16x16x32_bf16 v[18:21], v[154:157], v[224:227], v[18:21]
	v_mfma_f32_16x16x32_bf16 v[14:17], v[162:165], v[224:227], v[14:17]
	v_mfma_f32_16x16x32_bf16 v[14:17], v[158:161], v[220:223], v[14:17]
	v_mfma_f32_16x16x32_bf16 v[10:13], v[174:177], v[220:223], v[10:13]
	v_mfma_f32_16x16x32_bf16 v[10:13], v[178:181], v[224:227], v[10:13]
	v_mfma_f32_16x16x32_bf16 v[4:7], v[182:185], v[220:223], v[6:9]
	v_mfma_f32_16x16x32_bf16 v[4:7], v[186:189], v[224:227], v[4:7]
	s_setprio 0
	s_add_i32 s0, 0, 0x18000
	v_add_u32_e32 v3, s0, v167
	s_add_i32 s1, 0, 0x1c000
	ds_read_b128 v[150:153], v3
	ds_read_b128 v[154:157], v3 offset:1024
	ds_read_b128 v[158:161], v3 offset:2048
	ds_read_b128 v[162:165], v3 offset:3072
	v_add_u32_e32 v3, s1, v167
	ds_read_b128 v[174:177], v3
	ds_read_b128 v[178:181], v3 offset:1024
	ds_read_b128 v[182:185], v3 offset:2048
	ds_read_b128 v[186:189], v3 offset:3072
	ds_read_b128 v[190:193], v171 offset:32768
	ds_read_b128 v[196:199], v171 offset:33792
	ds_read_b128 v[200:203], v171 offset:34816
	ds_read_b128 v[204:207], v171 offset:35840
	ds_read_b128 v[208:211], v171 offset:36864
	ds_read_b128 v[212:215], v171 offset:37888
	ds_read_b128 v[220:223], v171 offset:38912
	ds_read_b128 v[224:227], v171 offset:39936
	s_add_u32 vcc_lo, s92, 0x100000
	s_addc_u32 vcc_hi, s93, 0
	s_mov_b32 m0, s27
	s_nop 0
	global_load_lds_dwordx4 v134, s[92:93]
	s_add_i32 m0, s27, 0x2000
	s_nop 0
	global_load_lds_dwordx4 v138, s[92:93]
	s_add_i32 m0, s27, 0x4000
	s_nop 0
	global_load_lds_dwordx4 v134, vcc
	s_add_i32 m0, s27, 0x6000
	s_nop 0
	global_load_lds_dwordx4 v138, vcc
	s_sleep 2
	s_waitcnt lgkmcnt(0)
	s_waitcnt vmcnt(8)
	s_barrier
; #define PG8_STAGE(bufoff, gbase, voff) do { _Pragma("unroll") for (int _i = 0; _i < 2; ++_i) \
;         __builtin_amdgcn_global_load_lds((const unsigned*)((const char*)(gbase) + (voff)[_i]), (PG8_LAS unsigned*)(lds + (bufoff) + ldsw + _i * 8192), 16, 0, 0); } while (0)
; #define PG8_LDA(dst, b, h) do { _Pragma("unroll") for (int m = 0; m < 4; ++m) _Pragma("unroll") for (int k = 0; k < 2; ++k) dst[m][k] = *(const PG8_LAS bf16x8*)(lds + PG8_SA(b, h) + aoff + m * 2048 + k * 1024); } while (0)
; #define PG8_MMA(ai, bj, At, Bt) do { __builtin_amdgcn_s_setprio(1); _Pragma("unroll") for (int m = 0; m < 4; ++m) _Pragma("unroll") for (int n = 0; n < 2; ++n) _Pragma("unroll") for (int k = 0; k < 2; ++k) \
;         acc[ai][bj][m][n] = __builtin_amdgcn_mfma_f32_16x16x32_bf16(Bt[n][k], At[m][k], acc[ai][bj][m][n], 0, 0, 0); __builtin_amdgcn_s_setprio(0); } while (0)
; #define PG8_WAIT_V(n) asm volatile("s_waitcnt vmcnt(" #n ")" ::: "memory")
; #define PG8_WAIT_L(n) asm volatile("s_waitcnt lgkmcnt(" #n ")" ::: "memory")
; #define PG8_BAR __builtin_amdgcn_s_barrier()
; #define PG8_SCHED __builtin_amdgcn_sched_barrier(0)
; template <class Epi, class Sched, bool ALIGN_EPI = false, bool SP2 = false>
; __device__ __forceinline__ void gemm_phase(PG8_LAS unsigned char* lds, const Gemm g, const Sched& S, const Epi& E) {
;     ...
;             PG8_WAIT_V(8); PG8_WAIT_L(0); PG8_BAR; PG8_MMA(0, 0, At, B0); PG8_MMA(0, 1, At, B1); PG8_BAR; PG8_SCHED;
;             PG8_LDA(At, 1, 1); PG8_STAGE(PG8_SB(1, 0), b3, voffB); PG8_STAGE(PG8_SB(1, 1), b3 + hstep, voffB); PG8_STAGE(PG8_SA(1, 0), a3, voffA);
;             PG8_WAIT_V(8); PG8_WAIT_L(0); PG8_BAR; PG8_MMA(1, 0, At, B0); PG8_MMA(1, 1, At, B1); PG8_BAR; PG8_SCHED;
	s_setprio 2
	v_mfma_f32_16x16x32_bf16 v[38:41], v[150:153], v[190:193], v[38:41]
	v_mfma_f32_16x16x32_bf16 v[38:41], v[154:157], v[196:199], v[38:41]
	v_mfma_f32_16x16x32_bf16 v[30:33], v[162:165], v[196:199], v[30:33]
	v_mfma_f32_16x16x32_bf16 v[30:33], v[158:161], v[190:193], v[30:33]
	v_mfma_f32_16x16x32_bf16 v[50:53], v[174:177], v[190:193], v[50:53]
	v_mfma_f32_16x16x32_bf16 v[50:53], v[178:181], v[196:199], v[50:53]
	v_mfma_f32_16x16x32_bf16 v[46:49], v[186:189], v[196:199], v[46:49]
	v_mfma_f32_16x16x32_bf16 v[46:49], v[182:185], v[190:193], v[46:49]
	v_mfma_f32_16x16x32_bf16 v[130:133], v[150:153], v[200:203], v[130:133]
	v_mfma_f32_16x16x32_bf16 v[130:133], v[154:157], v[204:207], v[130:133]
	v_mfma_f32_16x16x32_bf16 v[126:129], v[162:165], v[204:207], v[126:129]
	v_mfma_f32_16x16x32_bf16 v[126:129], v[158:161], v[200:203], v[126:129]
	v_mfma_f32_16x16x32_bf16 v[122:125], v[174:177], v[200:203], v[122:125]
	v_mfma_f32_16x16x32_bf16 v[122:125], v[178:181], v[204:207], v[122:125]
	v_mfma_f32_16x16x32_bf16 v[118:121], v[186:189], v[204:207], v[118:121]
	v_mfma_f32_16x16x32_bf16 v[118:121], v[182:185], v[200:203], v[118:121]
	v_mfma_f32_16x16x32_bf16 v[114:117], v[150:153], v[208:211], v[114:117]
	v_mfma_f32_16x16x32_bf16 v[114:117], v[154:157], v[212:215], v[114:117]
	v_mfma_f32_16x16x32_bf16 v[110:113], v[162:165], v[212:215], v[110:113]
	v_mfma_f32_16x16x32_bf16 v[110:113], v[158:161], v[208:211], v[110:113]
	v_mfma_f32_16x16x32_bf16 v[106:109], v[174:177], v[208:211], v[106:109]
	v_mfma_f32_16x16x32_bf16 v[106:109], v[178:181], v[212:215], v[106:109]
	v_mfma_f32_16x16x32_bf16 v[102:105], v[186:189], v[212:215], v[102:105]
	v_mfma_f32_16x16x32_bf16 v[102:105], v[182:185], v[208:211], v[102:105]
	v_mfma_f32_16x16x32_bf16 v[98:101], v[150:153], v[220:223], v[98:101]
	v_mfma_f32_16x16x32_bf16 v[98:101], v[154:157], v[224:227], v[98:101]
	v_mfma_f32_16x16x32_bf16 v[94:97], v[162:165], v[224:227], v[94:97]
	v_mfma_f32_16x16x32_bf16 v[94:97], v[158:161], v[220:223], v[94:97]
	v_mfma_f32_16x16x32_bf16 v[90:93], v[174:177], v[220:223], v[90:93]
	v_mfma_f32_16x16x32_bf16 v[90:93], v[178:181], v[224:227], v[90:93]
	v_mfma_f32_16x16x32_bf16 v[86:89], v[186:189], v[224:227], v[86:89]
	v_mfma_f32_16x16x32_bf16 v[86:89], v[182:185], v[220:223], v[86:89]
	s_setprio 0
	ds_read_b128 v[190:193], v171 offset:49152
	ds_read_b128 v[196:199], v171 offset:50176
	ds_read_b128 v[200:203], v171 offset:51200
	ds_read_b128 v[204:207], v171 offset:52224
	ds_read_b128 v[208:211], v171 offset:53248
	ds_read_b128 v[212:215], v171 offset:54272
	ds_read_b128 v[220:223], v171 offset:55296
	ds_read_b128 v[224:227], v171 offset:56320
	s_add_u32 s0, s90, 0x80
	s_addc_u32 s1, s91, 0
	s_add_u32 vcc_lo, s0, 0x100000
	s_addc_u32 vcc_hi, s1, 0
	s_add_i32 m0, s27, 0x18000
	s_nop 0
	global_load_lds_dwordx4 v136, s[0:1]
	s_add_i32 m0, s27, 0x1a000
	s_nop 0
	global_load_lds_dwordx4 v140, s[0:1]
	s_add_i32 m0, s27, 0x1c000
	s_nop 0
	global_load_lds_dwordx4 v136, vcc
	s_add_i32 m0, s27, 0x1e000
	s_nop 0
	global_load_lds_dwordx4 v140, vcc
	s_sleep 2
	s_waitcnt lgkmcnt(0)
	s_waitcnt vmcnt(6)
	s_barrier
	s_setprio 2
	v_mfma_f32_16x16x32_bf16 v[82:85], v[150:153], v[190:193], v[82:85]
	v_mfma_f32_16x16x32_bf16 v[82:85], v[154:157], v[196:199], v[82:85]
	v_mfma_f32_16x16x32_bf16 v[78:81], v[162:165], v[196:199], v[78:81]
	v_mfma_f32_16x16x32_bf16 v[78:81], v[158:161], v[190:193], v[78:81]
	v_mfma_f32_16x16x32_bf16 v[74:77], v[174:177], v[190:193], v[74:77]
	v_mfma_f32_16x16x32_bf16 v[74:77], v[178:181], v[196:199], v[74:77]
	v_mfma_f32_16x16x32_bf16 v[70:73], v[186:189], v[196:199], v[70:73]
	v_mfma_f32_16x16x32_bf16 v[70:73], v[182:185], v[190:193], v[70:73]
	v_mfma_f32_16x16x32_bf16 v[66:69], v[150:153], v[200:203], v[66:69]
	v_mfma_f32_16x16x32_bf16 v[66:69], v[154:157], v[204:207], v[66:69]
	v_mfma_f32_16x16x32_bf16 v[62:65], v[162:165], v[204:207], v[62:65]
	v_mfma_f32_16x16x32_bf16 v[62:65], v[158:161], v[200:203], v[62:65]
	v_mfma_f32_16x16x32_bf16 v[58:61], v[174:177], v[200:203], v[58:61]
	v_mfma_f32_16x16x32_bf16 v[58:61], v[178:181], v[204:207], v[58:61]
	v_mfma_f32_16x16x32_bf16 v[54:57], v[186:189], v[204:207], v[54:57]
	v_mfma_f32_16x16x32_bf16 v[54:57], v[182:185], v[200:203], v[54:57]
	v_mfma_f32_16x16x32_bf16 v[42:45], v[150:153], v[208:211], v[42:45]
	v_mfma_f32_16x16x32_bf16 v[42:45], v[154:157], v[212:215], v[42:45]
	v_mfma_f32_16x16x32_bf16 v[34:37], v[162:165], v[212:215], v[34:37]
	v_mfma_f32_16x16x32_bf16 v[34:37], v[158:161], v[208:211], v[34:37]
	v_mfma_f32_16x16x32_bf16 v[26:29], v[174:177], v[208:211], v[26:29]
	v_mfma_f32_16x16x32_bf16 v[26:29], v[178:181], v[212:215], v[26:29]
	v_mfma_f32_16x16x32_bf16 v[22:25], v[186:189], v[212:215], v[22:25]
	v_mfma_f32_16x16x32_bf16 v[22:25], v[182:185], v[208:211], v[22:25]
	v_mfma_f32_16x16x32_bf16 v[18:21], v[150:153], v[220:223], v[18:21]
	v_mfma_f32_16x16x32_bf16 v[18:21], v[154:157], v[224:227], v[18:21]
	v_mfma_f32_16x16x32_bf16 v[14:17], v[162:165], v[224:227], v[14:17]
	v_mfma_f32_16x16x32_bf16 v[14:17], v[158:161], v[220:223], v[14:17]
	v_mfma_f32_16x16x32_bf16 v[8:11], v[174:177], v[220:223], v[10:13]
	v_mfma_f32_16x16x32_bf16 v[10:13], v[178:181], v[224:227], v[8:11]
	v_mfma_f32_16x16x32_bf16 v[4:7], v[182:185], v[220:223], v[4:7]
	v_mfma_f32_16x16x32_bf16 v[6:9], v[186:189], v[224:227], v[4:7]
	s_setprio 0
	s_add_i32 s23, s23, 2
	s_add_u32 s88, s88, 0x100
	s_addc_u32 s89, s89, 0
	s_add_u32 s9, s9, 0x100
	s_addc_u32 s21, s21, 0
	s_cmp_gt_u32 s23, 61
	s_cbranch_scc0 .Lip_h1

; #define PG8_STAGE(bufoff, gbase, voff) do { _Pragma("unroll") for (int _i = 0; _i < 2; ++_i) \
;         __builtin_amdgcn_global_load_lds((const unsigned*)((const char*)(gbase) + (voff)[_i]), (PG8_LAS unsigned*)(lds + (bufoff) + ldsw + _i * 8192), 16, 0, 0); } while (0)
; #define PG8_LDA(dst, b, h) do { _Pragma("unroll") for (int m = 0; m < 4; ++m) _Pragma("unroll") for (int k = 0; k < 2; ++k) dst[m][k] = *(const PG8_LAS bf16x8*)(lds + PG8_SA(b, h) + aoff + m * 2048 + k * 1024); } while (0)
; #define PG8_LDB(dst, b, h) do { _Pragma("unroll") for (int n = 0; n < 2; ++n) _Pragma("unroll") for (int k = 0; k < 2; ++k) dst[n][k] = *(const PG8_LAS bf16x8*)(lds + PG8_SB(b, h) + boff + n * 2048 + k * 1024); } while (0)
; #define PG8_MMA(ai, bj, At, Bt) do { __builtin_amdgcn_s_setprio(1); _Pragma("unroll") for (int m = 0; m < 4; ++m) _Pragma("unroll") for (int n = 0; n < 2; ++n) _Pragma("unroll") for (int k = 0; k < 2; ++k) \
;         acc[ai][bj][m][n] = __builtin_amdgcn_mfma_f32_16x16x32_bf16(Bt[n][k], At[m][k], acc[ai][bj][m][n], 0, 0, 0); __builtin_amdgcn_s_setprio(0); } while (0)
; #define PG8_WAIT_V(n) asm volatile("s_waitcnt vmcnt(" #n ")" ::: "memory")
; #define PG8_WAIT_L(n) asm volatile("s_waitcnt lgkmcnt(" #n ")" ::: "memory")
; #define PG8_BAR __builtin_amdgcn_s_barrier()
; #define PG8_SCHED __builtin_amdgcn_sched_barrier(0)
; template <class Epi, class Sched, bool ALIGN_EPI = false, bool SP2 = false>
; __device__ __forceinline__ void gemm_phase(PG8_LAS unsigned char* lds, const Gemm g, const Sched& S, const Epi& E) {
;     ...
;             PG8_LDB(B0, 0, 0); PG8_LDB(B1, 0, 1); PG8_SCHED; PG8_LDA(At, 0, 0); PG8_STAGE(PG8_SA(1, 1), a1 + hstep, voffA);
;             PG8_WAIT_V(8); PG8_WAIT_L(0); PG8_BAR; PG8_MMA(0, 0, At, B0); PG8_MMA(0, 1, At, B1); PG8_BAR; PG8_SCHED;
;             PG8_LDA(At, 0, 1); PG8_STAGE(PG8_SB(0, 0), b2, voffB); PG8_STAGE(PG8_SB(0, 1), b2 + hstep, voffB); PG8_STAGE(PG8_SA(0, 0), a2, voffA);
;             PG8_WAIT_V(8); PG8_WAIT_L(0); PG8_BAR; PG8_MMA(1, 0, At, B0); PG8_MMA(1, 1, At, B1); PG8_BAR; PG8_SCHED;
.LBB0_911:
	v_add_u32_e32 v3, s83, v219
	ds_read_b128 v[98:101], v3
	ds_read_b128 v[102:105], v3 offset:1024
	ds_read_b128 v[106:109], v3 offset:2048
	ds_read_b128 v[166:169], v3 offset:3072
	v_add_u32_e32 v3, s86, v219
	s_add_u32 s62, s58, s60
	ds_read_b128 v[170:173], v3
	ds_read_b128 v[174:177], v3 offset:1024
	ds_read_b128 v[178:181], v3 offset:2048
	ds_read_b128 v[182:185], v3 offset:3072
	s_addc_u32 s63, s59, s61
	s_add_u32 s62, s62, 0x100
	s_addc_u32 s63, s63, 0
	s_add_u32 s93, s90, s60
	s_addc_u32 s94, s91, s61
	s_cmpk_eq_i32 s60, 0x1f00
	s_cselect_b32 s65, s19, s63
	s_cselect_b32 s64, s21, s62
	s_cselect_b32 s63, s53, s94
	s_cselect_b32 s62, s57, s93
	v_lshl_add_u64 v[4:5], v[94:95], 0, s[60:61]
	s_add_i32 m0, s24, 0xc000
	ds_read_b128 v[186:189], v244
	ds_read_b128 v[190:193], v244 offset:1024
	ds_read_b128 v[196:199], v244 offset:2048
	ds_read_b128 v[200:203], v244 offset:3072
	ds_read_b128 v[204:207], v244 offset:4096
	ds_read_b128 v[208:211], v244 offset:5120
	ds_read_b128 v[212:215], v244 offset:6144
	ds_read_b128 v[246:249], v244 offset:7168
	global_load_lds_dwordx4 v[4:5], off
	v_lshl_add_u64 v[4:5], v[96:97], 0, s[60:61]
	s_add_i32 m0, s24, 0xe000
	s_nop 0
	global_load_lds_dwordx4 v[4:5], off
	s_waitcnt vmcnt(8)
	s_waitcnt lgkmcnt(0)
	s_barrier
	s_setprio 1
	s_waitcnt lgkmcnt(0)
	v_mfma_f32_16x16x32_bf16 v[146:149], v[98:101], v[186:189], v[146:149]
	v_mfma_f32_16x16x32_bf16 v[146:149], v[102:105], v[190:193], v[146:149]
	v_mfma_f32_16x16x32_bf16 v[142:145], v[166:169], v[190:193], v[142:145]
	v_mfma_f32_16x16x32_bf16 v[142:145], v[106:109], v[186:189], v[142:145]
	v_mfma_f32_16x16x32_bf16 v[66:69], v[170:173], v[186:189], v[66:69]
	v_mfma_f32_16x16x32_bf16 v[66:69], v[174:177], v[190:193], v[66:69]
	v_mfma_f32_16x16x32_bf16 v[62:65], v[182:185], v[190:193], v[62:65]
	v_mfma_f32_16x16x32_bf16 v[62:65], v[178:181], v[186:189], v[62:65]
	v_mfma_f32_16x16x32_bf16 v[138:141], v[98:101], v[196:199], v[138:141]
	v_mfma_f32_16x16x32_bf16 v[138:141], v[102:105], v[200:203], v[138:141]
	v_mfma_f32_16x16x32_bf16 v[134:137], v[166:169], v[200:203], v[134:137]
	v_mfma_f32_16x16x32_bf16 v[134:137], v[106:109], v[196:199], v[134:137]
	v_mfma_f32_16x16x32_bf16 v[58:61], v[170:173], v[196:199], v[58:61]
	v_mfma_f32_16x16x32_bf16 v[58:61], v[174:177], v[200:203], v[58:61]
	v_mfma_f32_16x16x32_bf16 v[54:57], v[182:185], v[200:203], v[54:57]
	v_mfma_f32_16x16x32_bf16 v[54:57], v[178:181], v[196:199], v[54:57]
	s_setprio 0
	s_setprio 1
	v_mfma_f32_16x16x32_bf16 v[130:133], v[98:101], v[204:207], v[130:133]
	v_mfma_f32_16x16x32_bf16 v[130:133], v[102:105], v[208:211], v[130:133]
	v_mfma_f32_16x16x32_bf16 v[126:129], v[166:169], v[208:211], v[126:129]
	v_mfma_f32_16x16x32_bf16 v[126:129], v[106:109], v[204:207], v[126:129]
	v_mfma_f32_16x16x32_bf16 v[50:53], v[170:173], v[204:207], v[50:53]
	v_mfma_f32_16x16x32_bf16 v[50:53], v[174:177], v[208:211], v[50:53]
	v_mfma_f32_16x16x32_bf16 v[46:49], v[182:185], v[208:211], v[46:49]
	v_mfma_f32_16x16x32_bf16 v[46:49], v[178:181], v[204:207], v[46:49]
	v_mfma_f32_16x16x32_bf16 v[122:125], v[98:101], v[212:215], v[122:125]
	v_mfma_f32_16x16x32_bf16 v[122:125], v[102:105], v[246:249], v[122:125]
	v_mfma_f32_16x16x32_bf16 v[118:121], v[166:169], v[246:249], v[118:121]
	v_mfma_f32_16x16x32_bf16 v[118:121], v[106:109], v[212:215], v[118:121]
	v_mfma_f32_16x16x32_bf16 v[42:45], v[170:173], v[212:215], v[42:45]
	v_mfma_f32_16x16x32_bf16 v[42:45], v[174:177], v[246:249], v[42:45]
	v_mfma_f32_16x16x32_bf16 v[38:41], v[182:185], v[246:249], v[38:41]
	v_mfma_f32_16x16x32_bf16 v[38:41], v[178:181], v[212:215], v[38:41]
	s_setprio 0
	s_barrier
	s_add_i32 s93, s83, s2
	v_lshl_add_u64 v[216:217], s[62:63], 0, v[152:153]
	s_mov_b32 m0, s93
	ds_read_b128 v[186:189], v244 offset:16384
	ds_read_b128 v[190:193], v244 offset:17408
	ds_read_b128 v[196:199], v244 offset:18432
	ds_read_b128 v[200:203], v244 offset:19456
	ds_read_b128 v[204:207], v244 offset:20480
	ds_read_b128 v[208:211], v244 offset:21504
	ds_read_b128 v[212:215], v244 offset:22528
	ds_read_b128 v[246:249], v244 offset:23552
	global_load_lds_dwordx4 v[216:217], off
	s_add_i32 m0, s93, 0x2000
	s_add_u32 s94, s62, 0x100000
	v_lshl_add_u64 v[250:251], s[62:63], 0, v[156:157]
	s_addc_u32 s95, s63, 0
	s_add_i32 s93, s86, s2
	global_load_lds_dwordx4 v[250:251], off
	v_lshl_add_u64 v[4:5], s[94:95], 0, v[152:153]
	s_mov_b32 m0, s93
	v_lshl_add_u64 v[252:253], s[64:65], 0, v[150:151]
	global_load_lds_dwordx4 v[4:5], off
	v_lshl_add_u64 v[4:5], s[94:95], 0, v[156:157]
	s_add_i32 m0, s93, 0x2000
	v_lshl_add_u64 v[222:223], s[64:65], 0, v[154:155]
	global_load_lds_dwordx4 v[4:5], off
	s_mov_b32 m0, s24
	s_nop 0
	global_load_lds_dwordx4 v[252:253], off
	s_mov_b32 m0, s25
	s_nop 0
	global_load_lds_dwordx4 v[222:223], off
	s_waitcnt vmcnt(8)
	s_waitcnt lgkmcnt(0)
	s_barrier
; #define PG8_STAGE(bufoff, gbase, voff) do { _Pragma("unroll") for (int _i = 0; _i < 2; ++_i) \
;         __builtin_amdgcn_global_load_lds((const unsigned*)((const char*)(gbase) + (voff)[_i]), (PG8_LAS unsigned*)(lds + (bufoff) + ldsw + _i * 8192), 16, 0, 0); } while (0)
; #define PG8_LDA(dst, b, h) do { _Pragma("unroll") for (int m = 0; m < 4; ++m) _Pragma("unroll") for (int k = 0; k < 2; ++k) dst[m][k] = *(const PG8_LAS bf16x8*)(lds + PG8_SA(b, h) + aoff + m * 2048 + k * 1024); } while (0)
; #define PG8_LDB(dst, b, h) do { _Pragma("unroll") for (int n = 0; n < 2; ++n) _Pragma("unroll") for (int k = 0; k < 2; ++k) dst[n][k] = *(const PG8_LAS bf16x8*)(lds + PG8_SB(b, h) + boff + n * 2048 + k * 1024); } while (0)
; #define PG8_MMA(ai, bj, At, Bt) do { __builtin_amdgcn_s_setprio(1); _Pragma("unroll") for (int m = 0; m < 4; ++m) _Pragma("unroll") for (int n = 0; n < 2; ++n) _Pragma("unroll") for (int k = 0; k < 2; ++k) \
;         acc[ai][bj][m][n] = __builtin_amdgcn_mfma_f32_16x16x32_bf16(Bt[n][k], At[m][k], acc[ai][bj][m][n], 0, 0, 0); __builtin_amdgcn_s_setprio(0); } while (0)
; #define PG8_WAIT_V(n) asm volatile("s_waitcnt vmcnt(" #n ")" ::: "memory")
; #define PG8_WAIT_L(n) asm volatile("s_waitcnt lgkmcnt(" #n ")" ::: "memory")
; #define PG8_BAR __builtin_amdgcn_s_barrier()
; #define PG8_SCHED __builtin_amdgcn_sched_barrier(0)
; template <class Epi, class Sched, bool ALIGN_EPI = false, bool SP2 = false>
; __device__ __forceinline__ void gemm_phase(PG8_LAS unsigned char* lds, const Gemm g, const Sched& S, const Epi& E) {
;     ...
;             PG8_WAIT_V(8); PG8_WAIT_L(0); PG8_BAR; PG8_MMA(1, 0, At, B0); PG8_MMA(1, 1, At, B1); PG8_BAR; PG8_SCHED;
;             PG8_LDB(B0, 1, 0); PG8_LDB(B1, 1, 1); PG8_SCHED; PG8_LDA(At, 1, 0); PG8_STAGE(PG8_SA(0, 1), a2 + hstep, voffA);
;             PG8_WAIT_V(8); PG8_WAIT_L(0); PG8_BAR; PG8_MMA(0, 0, At, B0); PG8_MMA(0, 1, At, B1); PG8_BAR; PG8_SCHED;
	s_setprio 1
	s_waitcnt lgkmcnt(0)
	v_mfma_f32_16x16x32_bf16 v[114:117], v[98:101], v[186:189], v[114:117]
	v_mfma_f32_16x16x32_bf16 v[114:117], v[102:105], v[190:193], v[114:117]
	v_mfma_f32_16x16x32_bf16 v[110:113], v[166:169], v[190:193], v[110:113]
	v_mfma_f32_16x16x32_bf16 v[110:113], v[106:109], v[186:189], v[110:113]
	v_mfma_f32_16x16x32_bf16 v[34:37], v[170:173], v[186:189], v[34:37]
	v_mfma_f32_16x16x32_bf16 v[34:37], v[174:177], v[190:193], v[34:37]
	v_mfma_f32_16x16x32_bf16 v[30:33], v[182:185], v[190:193], v[30:33]
	v_mfma_f32_16x16x32_bf16 v[30:33], v[178:181], v[186:189], v[30:33]
	v_mfma_f32_16x16x32_bf16 v[90:93], v[98:101], v[196:199], v[90:93]
	v_mfma_f32_16x16x32_bf16 v[90:93], v[102:105], v[200:203], v[90:93]
	v_mfma_f32_16x16x32_bf16 v[86:89], v[166:169], v[200:203], v[86:89]
	v_mfma_f32_16x16x32_bf16 v[86:89], v[106:109], v[196:199], v[86:89]
	v_mfma_f32_16x16x32_bf16 v[26:29], v[170:173], v[196:199], v[26:29]
	v_mfma_f32_16x16x32_bf16 v[26:29], v[174:177], v[200:203], v[26:29]
	v_mfma_f32_16x16x32_bf16 v[22:25], v[182:185], v[200:203], v[22:25]
	v_mfma_f32_16x16x32_bf16 v[22:25], v[178:181], v[196:199], v[22:25]
	s_setprio 0
	s_setprio 1
	v_mfma_f32_16x16x32_bf16 v[82:85], v[98:101], v[204:207], v[82:85]
	v_mfma_f32_16x16x32_bf16 v[82:85], v[102:105], v[208:211], v[82:85]
	v_mfma_f32_16x16x32_bf16 v[78:81], v[166:169], v[208:211], v[78:81]
	v_mfma_f32_16x16x32_bf16 v[78:81], v[106:109], v[204:207], v[78:81]
	v_mfma_f32_16x16x32_bf16 v[18:21], v[170:173], v[204:207], v[18:21]
	v_mfma_f32_16x16x32_bf16 v[18:21], v[174:177], v[208:211], v[18:21]
	v_mfma_f32_16x16x32_bf16 v[14:17], v[182:185], v[208:211], v[14:17]
	v_mfma_f32_16x16x32_bf16 v[14:17], v[178:181], v[204:207], v[14:17]
	v_mfma_f32_16x16x32_bf16 v[74:77], v[98:101], v[212:215], v[74:77]
	v_mfma_f32_16x16x32_bf16 v[74:77], v[102:105], v[246:249], v[74:77]
	v_mfma_f32_16x16x32_bf16 v[70:73], v[166:169], v[246:249], v[70:73]
	v_mfma_f32_16x16x32_bf16 v[70:73], v[106:109], v[212:215], v[70:73]
	v_mfma_f32_16x16x32_bf16 v[10:13], v[170:173], v[212:215], v[10:13]
	v_mfma_f32_16x16x32_bf16 v[10:13], v[174:177], v[246:249], v[10:13]
	v_mfma_f32_16x16x32_bf16 v[4:7], v[178:181], v[212:215], v[6:9]
	v_mfma_f32_16x16x32_bf16 v[4:7], v[182:185], v[246:249], v[4:7]
	s_setprio 0
	s_barrier
	s_add_i32 s93, 0, 0x18000
	v_add_u32_e32 v3, s93, v219
	s_add_i32 s94, 0, 0x1c000
	ds_read_b128 v[98:101], v3
	ds_read_b128 v[102:105], v3 offset:1024
	ds_read_b128 v[106:109], v3 offset:2048
	ds_read_b128 v[166:169], v3 offset:3072
	v_add_u32_e32 v3, s94, v219
	ds_read_b128 v[170:173], v3
	ds_read_b128 v[174:177], v3 offset:1024
	ds_read_b128 v[178:181], v3 offset:2048
	ds_read_b128 v[182:185], v3 offset:3072
	s_add_u32 s64, s64, 0x100000
	s_addc_u32 s65, s65, 0
	s_mov_b32 m0, s26
	v_lshl_add_u64 v[8:9], s[64:65], 0, v[150:151]
	ds_read_b128 v[186:189], v244 offset:32768
	ds_read_b128 v[190:193], v244 offset:33792
	ds_read_b128 v[196:199], v244 offset:34816
	ds_read_b128 v[200:203], v244 offset:35840
	ds_read_b128 v[204:207], v244 offset:36864
	ds_read_b128 v[208:211], v244 offset:37888
	ds_read_b128 v[212:215], v244 offset:38912
	ds_read_b128 v[246:249], v244 offset:39936
	global_load_lds_dwordx4 v[8:9], off
	v_lshl_add_u64 v[8:9], s[64:65], 0, v[154:155]
	s_mov_b32 m0, s27
	s_nop 0
	global_load_lds_dwordx4 v[8:9], off
	s_waitcnt vmcnt(8)
	s_waitcnt lgkmcnt(0)
	s_barrier
	s_setprio 1
	s_waitcnt lgkmcnt(0)
	v_mfma_f32_16x16x32_bf16 v[146:149], v[98:101], v[186:189], v[146:149]
	v_mfma_f32_16x16x32_bf16 v[146:149], v[102:105], v[190:193], v[146:149]
	v_mfma_f32_16x16x32_bf16 v[142:145], v[166:169], v[190:193], v[142:145]
	v_mfma_f32_16x16x32_bf16 v[142:145], v[106:109], v[186:189], v[142:145]
	v_mfma_f32_16x16x32_bf16 v[66:69], v[170:173], v[186:189], v[66:69]
	v_mfma_f32_16x16x32_bf16 v[66:69], v[174:177], v[190:193], v[66:69]
	v_mfma_f32_16x16x32_bf16 v[62:65], v[182:185], v[190:193], v[62:65]
	v_mfma_f32_16x16x32_bf16 v[62:65], v[178:181], v[186:189], v[62:65]
	v_mfma_f32_16x16x32_bf16 v[138:141], v[98:101], v[196:199], v[138:141]
	v_mfma_f32_16x16x32_bf16 v[138:141], v[102:105], v[200:203], v[138:141]
	v_mfma_f32_16x16x32_bf16 v[134:137], v[166:169], v[200:203], v[134:137]
	v_mfma_f32_16x16x32_bf16 v[134:137], v[106:109], v[196:199], v[134:137]
	v_mfma_f32_16x16x32_bf16 v[58:61], v[170:173], v[196:199], v[58:61]
	v_mfma_f32_16x16x32_bf16 v[58:61], v[174:177], v[200:203], v[58:61]
	v_mfma_f32_16x16x32_bf16 v[54:57], v[182:185], v[200:203], v[54:57]
	v_mfma_f32_16x16x32_bf16 v[54:57], v[178:181], v[196:199], v[54:57]
	s_setprio 0
	s_setprio 1
	v_mfma_f32_16x16x32_bf16 v[130:133], v[98:101], v[204:207], v[130:133]
	v_mfma_f32_16x16x32_bf16 v[130:133], v[102:105], v[208:211], v[130:133]
	v_mfma_f32_16x16x32_bf16 v[126:129], v[166:169], v[208:211], v[126:129]
	v_mfma_f32_16x16x32_bf16 v[126:129], v[106:109], v[204:207], v[126:129]
	v_mfma_f32_16x16x32_bf16 v[50:53], v[170:173], v[204:207], v[50:53]
	v_mfma_f32_16x16x32_bf16 v[50:53], v[174:177], v[208:211], v[50:53]
	v_mfma_f32_16x16x32_bf16 v[46:49], v[182:185], v[208:211], v[46:49]
	v_mfma_f32_16x16x32_bf16 v[46:49], v[178:181], v[204:207], v[46:49]
	v_mfma_f32_16x16x32_bf16 v[122:125], v[98:101], v[212:215], v[122:125]
	v_mfma_f32_16x16x32_bf16 v[122:125], v[102:105], v[246:249], v[122:125]
	v_mfma_f32_16x16x32_bf16 v[118:121], v[166:169], v[246:249], v[118:121]
	v_mfma_f32_16x16x32_bf16 v[118:121], v[106:109], v[212:215], v[118:121]
	v_mfma_f32_16x16x32_bf16 v[42:45], v[170:173], v[212:215], v[42:45]
	v_mfma_f32_16x16x32_bf16 v[42:45], v[174:177], v[246:249], v[42:45]
	v_mfma_f32_16x16x32_bf16 v[38:41], v[182:185], v[246:249], v[38:41]
	v_mfma_f32_16x16x32_bf16 v[38:41], v[178:181], v[212:215], v[38:41]
	s_setprio 0
	s_barrier
; #define PG8_STAGE(bufoff, gbase, voff) do { _Pragma("unroll") for (int _i = 0; _i < 2; ++_i) \
;         __builtin_amdgcn_global_load_lds((const unsigned*)((const char*)(gbase) + (voff)[_i]), (PG8_LAS unsigned*)(lds + (bufoff) + ldsw + _i * 8192), 16, 0, 0); } while (0)
; #define PG8_LDA(dst, b, h) do { _Pragma("unroll") for (int m = 0; m < 4; ++m) _Pragma("unroll") for (int k = 0; k < 2; ++k) dst[m][k] = *(const PG8_LAS bf16x8*)(lds + PG8_SA(b, h) + aoff + m * 2048 + k * 1024); } while (0)
; #define PG8_MMA(ai, bj, At, Bt) do { __builtin_amdgcn_s_setprio(1); _Pragma("unroll") for (int m = 0; m < 4; ++m) _Pragma("unroll") for (int n = 0; n < 2; ++n) _Pragma("unroll") for (int k = 0; k < 2; ++k) \
;         acc[ai][bj][m][n] = __builtin_amdgcn_mfma_f32_16x16x32_bf16(Bt[n][k], At[m][k], acc[ai][bj][m][n], 0, 0, 0); __builtin_amdgcn_s_setprio(0); } while (0)
; #define PG8_WAIT_V(n) asm volatile("s_waitcnt vmcnt(" #n ")" ::: "memory")
; #define PG8_WAIT_L(n) asm volatile("s_waitcnt lgkmcnt(" #n ")" ::: "memory")
; #define PG8_BAR __builtin_amdgcn_s_barrier()
; #define PG8_SCHED __builtin_amdgcn_sched_barrier(0)
; template <class Epi, class Sched, bool ALIGN_EPI = false, bool SP2 = false>
; __device__ __forceinline__ void gemm_phase(PG8_LAS unsigned char* lds, const Gemm g, const Sched& S, const Epi& E) {
;     ...
;             PG8_LDA(At, 1, 1); PG8_STAGE(PG8_SB(1, 0), b3, voffB); PG8_STAGE(PG8_SB(1, 1), b3 + hstep, voffB); PG8_STAGE(PG8_SA(1, 0), a3, voffA);
;             PG8_WAIT_V(8); PG8_WAIT_L(0); PG8_BAR; PG8_MMA(1, 0, At, B0); PG8_MMA(1, 1, At, B1); PG8_BAR; PG8_SCHED;
	s_add_i32 s64, s93, s2
	v_lshl_add_u64 v[8:9], v[216:217], 0, s[14:15]
	s_mov_b32 m0, s64
	ds_read_b128 v[186:189], v244 offset:49152
	ds_read_b128 v[190:193], v244 offset:50176
	ds_read_b128 v[196:199], v244 offset:51200
	ds_read_b128 v[200:203], v244 offset:52224
	ds_read_b128 v[204:207], v244 offset:53248
	ds_read_b128 v[208:211], v244 offset:54272
	ds_read_b128 v[212:215], v244 offset:55296
	ds_read_b128 v[246:249], v244 offset:56320
	global_load_lds_dwordx4 v[8:9], off
	s_add_i32 m0, s64, 0x2000
	s_add_u32 s62, s62, 0x100080
	v_lshl_add_u64 v[8:9], v[250:251], 0, s[14:15]
	s_addc_u32 s63, s63, 0
	s_add_i32 s64, s94, s2
	global_load_lds_dwordx4 v[8:9], off
	v_lshl_add_u64 v[8:9], s[62:63], 0, v[152:153]
	s_mov_b32 m0, s64
	s_nop 0
	global_load_lds_dwordx4 v[8:9], off
	v_lshl_add_u64 v[8:9], s[62:63], 0, v[156:157]
	s_add_i32 m0, s64, 0x2000
	s_nop 0
	global_load_lds_dwordx4 v[8:9], off
	v_lshl_add_u64 v[8:9], v[252:253], 0, s[14:15]
	s_mov_b32 m0, s66
	s_nop 0
	global_load_lds_dwordx4 v[8:9], off
	v_lshl_add_u64 v[8:9], v[222:223], 0, s[14:15]
	s_mov_b32 m0, s67
	s_nop 0
	global_load_lds_dwordx4 v[8:9], off
	s_waitcnt vmcnt(8)
	s_waitcnt lgkmcnt(0)
	s_barrier
	s_setprio 1
	s_waitcnt lgkmcnt(0)
	v_mfma_f32_16x16x32_bf16 v[114:117], v[98:101], v[186:189], v[114:117]
	v_mfma_f32_16x16x32_bf16 v[114:117], v[102:105], v[190:193], v[114:117]
	v_mfma_f32_16x16x32_bf16 v[110:113], v[166:169], v[190:193], v[110:113]
	v_mfma_f32_16x16x32_bf16 v[110:113], v[106:109], v[186:189], v[110:113]
	v_mfma_f32_16x16x32_bf16 v[34:37], v[170:173], v[186:189], v[34:37]
	v_mfma_f32_16x16x32_bf16 v[34:37], v[174:177], v[190:193], v[34:37]
	v_mfma_f32_16x16x32_bf16 v[30:33], v[182:185], v[190:193], v[30:33]
	v_mfma_f32_16x16x32_bf16 v[30:33], v[178:181], v[186:189], v[30:33]
	v_mfma_f32_16x16x32_bf16 v[90:93], v[98:101], v[196:199], v[90:93]
	v_mfma_f32_16x16x32_bf16 v[90:93], v[102:105], v[200:203], v[90:93]
	v_mfma_f32_16x16x32_bf16 v[86:89], v[166:169], v[200:203], v[86:89]
	v_mfma_f32_16x16x32_bf16 v[86:89], v[106:109], v[196:199], v[86:89]
	v_mfma_f32_16x16x32_bf16 v[26:29], v[170:173], v[196:199], v[26:29]
	v_mfma_f32_16x16x32_bf16 v[26:29], v[174:177], v[200:203], v[26:29]
	v_mfma_f32_16x16x32_bf16 v[22:25], v[182:185], v[200:203], v[22:25]
	v_mfma_f32_16x16x32_bf16 v[22:25], v[178:181], v[196:199], v[22:25]
	s_setprio 0
	s_setprio 1
	v_mfma_f32_16x16x32_bf16 v[82:85], v[98:101], v[204:207], v[82:85]
	v_mfma_f32_16x16x32_bf16 v[82:85], v[102:105], v[208:211], v[82:85]
	v_mfma_f32_16x16x32_bf16 v[78:81], v[166:169], v[208:211], v[78:81]
	v_mfma_f32_16x16x32_bf16 v[78:81], v[106:109], v[204:207], v[78:81]
	v_mfma_f32_16x16x32_bf16 v[18:21], v[170:173], v[204:207], v[18:21]
	v_mfma_f32_16x16x32_bf16 v[18:21], v[174:177], v[208:211], v[18:21]
	v_mfma_f32_16x16x32_bf16 v[14:17], v[182:185], v[208:211], v[14:17]
	v_mfma_f32_16x16x32_bf16 v[14:17], v[178:181], v[204:207], v[14:17]
	v_mfma_f32_16x16x32_bf16 v[74:77], v[98:101], v[212:215], v[74:77]
	v_mfma_f32_16x16x32_bf16 v[74:77], v[102:105], v[246:249], v[74:77]
	v_mfma_f32_16x16x32_bf16 v[70:73], v[166:169], v[246:249], v[70:73]
	v_mfma_f32_16x16x32_bf16 v[70:73], v[106:109], v[212:215], v[70:73]
	v_mfma_f32_16x16x32_bf16 v[8:11], v[170:173], v[212:215], v[10:13]
	v_mfma_f32_16x16x32_bf16 v[10:13], v[174:177], v[246:249], v[8:11]
	v_mfma_f32_16x16x32_bf16 v[4:7], v[178:181], v[212:215], v[4:7]
	v_mfma_f32_16x16x32_bf16 v[6:9], v[182:185], v[246:249], v[4:7]
	s_setprio 0
	s_barrier
	s_add_i32 s92, s92, 2
	s_add_u32 s60, s60, 0x100
	s_addc_u32 s61, s61, 0
	s_cmp_gt_u32 s92, 61
	s_cbranch_scc1 .LBB0_914

; #define PG8_STAGE(bufoff, gbase, voff) do { _Pragma("unroll") for (int _i = 0; _i < 2; ++_i) \
;         __builtin_amdgcn_global_load_lds((const unsigned*)((const char*)(gbase) + (voff)[_i]), (PG8_LAS unsigned*)(lds + (bufoff) + ldsw + _i * 8192), 16, 0, 0); } while (0)
; #define PG8_LDA(dst, b, h) do { _Pragma("unroll") for (int m = 0; m < 4; ++m) _Pragma("unroll") for (int k = 0; k < 2; ++k) dst[m][k] = *(const PG8_LAS bf16x8*)(lds + PG8_SA(b, h) + aoff + m * 2048 + k * 1024); } while (0)
; #define PG8_LDB(dst, b, h) do { _Pragma("unroll") for (int n = 0; n < 2; ++n) _Pragma("unroll") for (int k = 0; k < 2; ++k) dst[n][k] = *(const PG8_LAS bf16x8*)(lds + PG8_SB(b, h) + boff + n * 2048 + k * 1024); } while (0)
; #define PG8_MMA(ai, bj, At, Bt) do { __builtin_amdgcn_s_setprio(1); _Pragma("unroll") for (int m = 0; m < 4; ++m) _Pragma("unroll") for (int n = 0; n < 2; ++n) _Pragma("unroll") for (int k = 0; k < 2; ++k) \
;         acc[ai][bj][m][n] = __builtin_amdgcn_mfma_f32_16x16x32_bf16(Bt[n][k], At[m][k], acc[ai][bj][m][n], 0, 0, 0); __builtin_amdgcn_s_setprio(0); } while (0)
; #define PG8_WAIT_V(n) asm volatile("s_waitcnt vmcnt(" #n ")" ::: "memory")
; #define PG8_WAIT_L(n) asm volatile("s_waitcnt lgkmcnt(" #n ")" ::: "memory")
; #define PG8_BAR __builtin_amdgcn_s_barrier()
; #define PG8_SCHED __builtin_amdgcn_sched_barrier(0)
; template <class Epi, class Sched, bool ALIGN_EPI = false, bool SP2 = false>
; __device__ __forceinline__ void gemm_phase(PG8_LAS unsigned char* lds, const Gemm g, const Sched& S, const Epi& E) {
;     ...
;             PG8_LDB(B0, 0, 0); PG8_LDB(B1, 0, 1); PG8_SCHED; PG8_LDA(At, 0, 0); PG8_STAGE(PG8_SA(1, 1), a1 + hstep, voffA);
;             PG8_WAIT_V(8); PG8_WAIT_L(0); PG8_BAR; PG8_MMA(0, 0, At, B0); PG8_MMA(0, 1, At, B1); PG8_BAR; PG8_SCHED;
;             PG8_LDA(At, 0, 1); PG8_STAGE(PG8_SB(0, 0), b2, voffB); PG8_STAGE(PG8_SB(0, 1), b2 + hstep, voffB); PG8_STAGE(PG8_SA(0, 0), a2, voffA);
;             PG8_WAIT_V(8); PG8_WAIT_L(0); PG8_BAR; PG8_MMA(1, 0, At, B0); PG8_MMA(1, 1, At, B1); PG8_BAR; PG8_SCHED;
.LBB0_1251:
	ds_read_b128 v[130:133], v177
	ds_read_b128 v[134:137], v177 offset:1024
	ds_read_b128 v[138:141], v177 offset:2048
	ds_read_b128 v[142:145], v177 offset:3072
	ds_read_b128 v[162:165], v178
	ds_read_b128 v[180:183], v178 offset:1024
	ds_read_b128 v[184:187], v178 offset:2048
	ds_read_b128 v[188:191], v178 offset:3072
	s_add_u32 s40, s36, 0xfff00080
	s_addc_u32 s41, s37, -1
	s_cmp_eq_u32 s58, 60
	s_cselect_b32 s43, s15, s41
	s_cselect_b32 s42, s17, s40
	s_cselect_b32 s41, s54, s57
	s_cselect_b32 s40, s55, s56
	ds_read_b128 v[196:199], v179
	ds_read_b128 v[200:203], v179 offset:1024
	ds_read_b128 v[204:207], v179 offset:2048
	ds_read_b128 v[208:211], v179 offset:3072
	ds_read_b128 v[212:215], v179 offset:4096
	ds_read_b128 v[220:223], v179 offset:5120
	ds_read_b128 v[224:227], v179 offset:6144
	ds_read_b128 v[228:231], v179 offset:7168
	s_add_i32 m0, s24, 0xc000
	s_nop 0
	global_load_lds_dwordx4 v146, s[36:37]
	s_add_i32 m0, s24, 0xe000
	s_nop 0
	global_load_lds_dwordx4 v150, s[36:37]
	s_waitcnt lgkmcnt(0)
	s_setprio 1
	v_mfma_f32_16x16x32_bf16 v[126:129], v[130:133], v[196:199], v[126:129]
	v_mfma_f32_16x16x32_bf16 v[126:129], v[134:137], v[200:203], v[126:129]
	v_mfma_f32_16x16x32_bf16 v[122:125], v[142:145], v[200:203], v[122:125]
	v_mfma_f32_16x16x32_bf16 v[122:125], v[138:141], v[196:199], v[122:125]
	v_mfma_f32_16x16x32_bf16 v[118:121], v[162:165], v[196:199], v[118:121]
	v_mfma_f32_16x16x32_bf16 v[118:121], v[180:183], v[200:203], v[118:121]
	v_mfma_f32_16x16x32_bf16 v[114:117], v[188:191], v[200:203], v[114:117]
	v_mfma_f32_16x16x32_bf16 v[114:117], v[184:187], v[196:199], v[114:117]
	v_mfma_f32_16x16x32_bf16 v[110:113], v[130:133], v[204:207], v[110:113]
	v_mfma_f32_16x16x32_bf16 v[110:113], v[134:137], v[208:211], v[110:113]
	v_mfma_f32_16x16x32_bf16 v[106:109], v[142:145], v[208:211], v[106:109]
	v_mfma_f32_16x16x32_bf16 v[106:109], v[138:141], v[204:207], v[106:109]
	v_mfma_f32_16x16x32_bf16 v[102:105], v[162:165], v[204:207], v[102:105]
	v_mfma_f32_16x16x32_bf16 v[102:105], v[180:183], v[208:211], v[102:105]
	v_mfma_f32_16x16x32_bf16 v[98:101], v[188:191], v[208:211], v[98:101]
	v_mfma_f32_16x16x32_bf16 v[98:101], v[184:187], v[204:207], v[98:101]
	v_mfma_f32_16x16x32_bf16 v[94:97], v[130:133], v[212:215], v[94:97]
	v_mfma_f32_16x16x32_bf16 v[94:97], v[134:137], v[220:223], v[94:97]
	v_mfma_f32_16x16x32_bf16 v[90:93], v[142:145], v[220:223], v[90:93]
	v_mfma_f32_16x16x32_bf16 v[90:93], v[138:141], v[212:215], v[90:93]
	v_mfma_f32_16x16x32_bf16 v[86:89], v[162:165], v[212:215], v[86:89]
	v_mfma_f32_16x16x32_bf16 v[86:89], v[180:183], v[220:223], v[86:89]
	v_mfma_f32_16x16x32_bf16 v[82:85], v[188:191], v[220:223], v[82:85]
	v_mfma_f32_16x16x32_bf16 v[82:85], v[184:187], v[212:215], v[82:85]
	v_mfma_f32_16x16x32_bf16 v[78:81], v[130:133], v[224:227], v[78:81]
	v_mfma_f32_16x16x32_bf16 v[78:81], v[134:137], v[228:231], v[78:81]
	v_mfma_f32_16x16x32_bf16 v[74:77], v[142:145], v[228:231], v[74:77]
	v_mfma_f32_16x16x32_bf16 v[74:77], v[138:141], v[224:227], v[74:77]
	v_mfma_f32_16x16x32_bf16 v[70:73], v[162:165], v[224:227], v[70:73]
	v_mfma_f32_16x16x32_bf16 v[70:73], v[180:183], v[228:231], v[70:73]
	v_mfma_f32_16x16x32_bf16 v[66:69], v[188:191], v[228:231], v[66:69]
	v_mfma_f32_16x16x32_bf16 v[66:69], v[184:187], v[224:227], v[66:69]
	s_setprio 0
	s_waitcnt vmcnt(8)
	s_barrier
	ds_read_b128 v[196:199], v179 offset:16384
	ds_read_b128 v[200:203], v179 offset:17408
	ds_read_b128 v[204:207], v179 offset:18432
	ds_read_b128 v[208:211], v179 offset:19456
	ds_read_b128 v[212:215], v179 offset:20480
	ds_read_b128 v[220:223], v179 offset:21504
	ds_read_b128 v[224:227], v179 offset:22528
	ds_read_b128 v[228:231], v179 offset:23552
	s_add_u32 vcc_lo, s40, 0x100000
	s_addc_u32 vcc_hi, s41, 0
	s_add_i32 m0, s24, 0x10000
	s_nop 0
	global_load_lds_dwordx4 v148, s[40:41]
	s_add_i32 m0, s24, 0x12000
	s_nop 0
	global_load_lds_dwordx4 v152, s[40:41]
	s_add_i32 m0, s24, 0x14000
	s_nop 0
	global_load_lds_dwordx4 v148, vcc
	s_add_i32 m0, s24, 0x16000
	s_nop 0
	global_load_lds_dwordx4 v152, vcc
	s_mov_b32 m0, s24
	s_nop 0
	global_load_lds_dwordx4 v146, s[42:43]
	s_add_i32 m0, s24, 0x2000
	s_nop 0
	global_load_lds_dwordx4 v150, s[42:43]
	s_waitcnt lgkmcnt(0)
	s_setprio 1
	v_mfma_f32_16x16x32_bf16 v[62:65], v[130:133], v[196:199], v[62:65]
	v_mfma_f32_16x16x32_bf16 v[62:65], v[134:137], v[200:203], v[62:65]
	v_mfma_f32_16x16x32_bf16 v[58:61], v[142:145], v[200:203], v[58:61]
	v_mfma_f32_16x16x32_bf16 v[58:61], v[138:141], v[196:199], v[58:61]
	v_mfma_f32_16x16x32_bf16 v[54:57], v[162:165], v[196:199], v[54:57]
	v_mfma_f32_16x16x32_bf16 v[54:57], v[180:183], v[200:203], v[54:57]
	v_mfma_f32_16x16x32_bf16 v[50:53], v[188:191], v[200:203], v[50:53]
	v_mfma_f32_16x16x32_bf16 v[50:53], v[184:187], v[196:199], v[50:53]
	v_mfma_f32_16x16x32_bf16 v[46:49], v[130:133], v[204:207], v[46:49]
	v_mfma_f32_16x16x32_bf16 v[46:49], v[134:137], v[208:211], v[46:49]
	v_mfma_f32_16x16x32_bf16 v[42:45], v[142:145], v[208:211], v[42:45]
	v_mfma_f32_16x16x32_bf16 v[42:45], v[138:141], v[204:207], v[42:45]
	v_mfma_f32_16x16x32_bf16 v[38:41], v[162:165], v[204:207], v[38:41]
	v_mfma_f32_16x16x32_bf16 v[38:41], v[180:183], v[208:211], v[38:41]
	v_mfma_f32_16x16x32_bf16 v[34:37], v[188:191], v[208:211], v[34:37]
	v_mfma_f32_16x16x32_bf16 v[34:37], v[184:187], v[204:207], v[34:37]
	v_mfma_f32_16x16x32_bf16 v[30:33], v[130:133], v[212:215], v[30:33]
	v_mfma_f32_16x16x32_bf16 v[30:33], v[134:137], v[220:223], v[30:33]
	v_mfma_f32_16x16x32_bf16 v[26:29], v[142:145], v[220:223], v[26:29]
	v_mfma_f32_16x16x32_bf16 v[26:29], v[138:141], v[212:215], v[26:29]
	v_mfma_f32_16x16x32_bf16 v[22:25], v[162:165], v[212:215], v[22:25]
	v_mfma_f32_16x16x32_bf16 v[22:25], v[180:183], v[220:223], v[22:25]
	v_mfma_f32_16x16x32_bf16 v[18:21], v[188:191], v[220:223], v[18:21]
	v_mfma_f32_16x16x32_bf16 v[18:21], v[184:187], v[212:215], v[18:21]
	v_mfma_f32_16x16x32_bf16 v[14:17], v[130:133], v[224:227], v[14:17]
	v_mfma_f32_16x16x32_bf16 v[14:17], v[134:137], v[228:231], v[14:17]
	v_mfma_f32_16x16x32_bf16 v[10:13], v[142:145], v[228:231], v[10:13]
	v_mfma_f32_16x16x32_bf16 v[10:13], v[138:141], v[224:227], v[10:13]
	v_mfma_f32_16x16x32_bf16 v[6:9], v[162:165], v[224:227], v[6:9]
	v_mfma_f32_16x16x32_bf16 v[6:9], v[180:183], v[228:231], v[6:9]
	v_mfma_f32_16x16x32_bf16 v[2:5], v[188:191], v[228:231], v[2:5]
	v_mfma_f32_16x16x32_bf16 v[2:5], v[184:187], v[224:227], v[2:5]
	s_setprio 0
	s_waitcnt vmcnt(8)
	s_barrier
; #define PG8_STAGE(bufoff, gbase, voff) do { _Pragma("unroll") for (int _i = 0; _i < 2; ++_i) \
;         __builtin_amdgcn_global_load_lds((const unsigned*)((const char*)(gbase) + (voff)[_i]), (PG8_LAS unsigned*)(lds + (bufoff) + ldsw + _i * 8192), 16, 0, 0); } while (0)
; #define PG8_LDA(dst, b, h) do { _Pragma("unroll") for (int m = 0; m < 4; ++m) _Pragma("unroll") for (int k = 0; k < 2; ++k) dst[m][k] = *(const PG8_LAS bf16x8*)(lds + PG8_SA(b, h) + aoff + m * 2048 + k * 1024); } while (0)
; #define PG8_LDB(dst, b, h) do { _Pragma("unroll") for (int n = 0; n < 2; ++n) _Pragma("unroll") for (int k = 0; k < 2; ++k) dst[n][k] = *(const PG8_LAS bf16x8*)(lds + PG8_SB(b, h) + boff + n * 2048 + k * 1024); } while (0)
; #define PG8_MMA(ai, bj, At, Bt) do { __builtin_amdgcn_s_setprio(1); _Pragma("unroll") for (int m = 0; m < 4; ++m) _Pragma("unroll") for (int n = 0; n < 2; ++n) _Pragma("unroll") for (int k = 0; k < 2; ++k) \
;         acc[ai][bj][m][n] = __builtin_amdgcn_mfma_f32_16x16x32_bf16(Bt[n][k], At[m][k], acc[ai][bj][m][n], 0, 0, 0); __builtin_amdgcn_s_setprio(0); } while (0)
; #define PG8_WAIT_V(n) asm volatile("s_waitcnt vmcnt(" #n ")" ::: "memory")
; #define PG8_WAIT_L(n) asm volatile("s_waitcnt lgkmcnt(" #n ")" ::: "memory")
; #define PG8_BAR __builtin_amdgcn_s_barrier()
; #define PG8_SCHED __builtin_amdgcn_sched_barrier(0)
; template <class Epi, class Sched, bool ALIGN_EPI = false, bool SP2 = false>
; __device__ __forceinline__ void gemm_phase(PG8_LAS unsigned char* lds, const Gemm g, const Sched& S, const Epi& E) {
;     ...
;             PG8_LDB(B0, 1, 0); PG8_LDB(B1, 1, 1); PG8_SCHED; PG8_LDA(At, 1, 0); PG8_STAGE(PG8_SA(0, 1), a2 + hstep, voffA);
;             PG8_WAIT_V(8); PG8_WAIT_L(0); PG8_BAR; PG8_MMA(0, 0, At, B0); PG8_MMA(0, 1, At, B1); PG8_BAR; PG8_SCHED;
;             PG8_LDA(At, 1, 1); PG8_STAGE(PG8_SB(1, 0), b3, voffB); PG8_STAGE(PG8_SB(1, 1), b3 + hstep, voffB); PG8_STAGE(PG8_SA(1, 0), a3, voffA);
;             PG8_WAIT_V(8); PG8_WAIT_L(0); PG8_BAR; PG8_MMA(1, 0, At, B0); PG8_MMA(1, 1, At, B1); PG8_BAR; PG8_SCHED;
	s_add_i32 s59, 0, 0x18000
	s_add_i32 s60, 0, 0x1c000
	v_add_u32_e32 v142, s59, v166
	v_add_u32_e32 v188, s60, v166
	ds_read_b128 v[130:133], v142
	ds_read_b128 v[134:137], v142 offset:1024
	ds_read_b128 v[138:141], v142 offset:2048
	ds_read_b128 v[142:145], v142 offset:3072
	ds_read_b128 v[162:165], v188
	ds_read_b128 v[180:183], v188 offset:1024
	ds_read_b128 v[184:187], v188 offset:2048
	ds_read_b128 v[188:191], v188 offset:3072
	ds_read_b128 v[196:199], v179 offset:32768
	ds_read_b128 v[200:203], v179 offset:33792
	ds_read_b128 v[204:207], v179 offset:34816
	ds_read_b128 v[208:211], v179 offset:35840
	ds_read_b128 v[212:215], v179 offset:36864
	ds_read_b128 v[220:223], v179 offset:37888
	ds_read_b128 v[224:227], v179 offset:38912
	ds_read_b128 v[228:231], v179 offset:39936
	s_add_u32 vcc_lo, s42, 0x100000
	s_addc_u32 vcc_hi, s43, 0
	s_add_i32 m0, s24, 0x4000
	s_nop 0
	global_load_lds_dwordx4 v146, vcc
	s_add_i32 m0, s24, 0x6000
	s_nop 0
	global_load_lds_dwordx4 v150, vcc
	s_waitcnt lgkmcnt(0)
	s_setprio 1
	v_mfma_f32_16x16x32_bf16 v[126:129], v[130:133], v[196:199], v[126:129]
	v_mfma_f32_16x16x32_bf16 v[126:129], v[134:137], v[200:203], v[126:129]
	v_mfma_f32_16x16x32_bf16 v[122:125], v[142:145], v[200:203], v[122:125]
	v_mfma_f32_16x16x32_bf16 v[122:125], v[138:141], v[196:199], v[122:125]
	v_mfma_f32_16x16x32_bf16 v[118:121], v[162:165], v[196:199], v[118:121]
	v_mfma_f32_16x16x32_bf16 v[118:121], v[180:183], v[200:203], v[118:121]
	v_mfma_f32_16x16x32_bf16 v[114:117], v[188:191], v[200:203], v[114:117]
	v_mfma_f32_16x16x32_bf16 v[114:117], v[184:187], v[196:199], v[114:117]
	v_mfma_f32_16x16x32_bf16 v[110:113], v[130:133], v[204:207], v[110:113]
	v_mfma_f32_16x16x32_bf16 v[110:113], v[134:137], v[208:211], v[110:113]
	v_mfma_f32_16x16x32_bf16 v[106:109], v[142:145], v[208:211], v[106:109]
	v_mfma_f32_16x16x32_bf16 v[106:109], v[138:141], v[204:207], v[106:109]
	v_mfma_f32_16x16x32_bf16 v[102:105], v[162:165], v[204:207], v[102:105]
	v_mfma_f32_16x16x32_bf16 v[102:105], v[180:183], v[208:211], v[102:105]
	v_mfma_f32_16x16x32_bf16 v[98:101], v[188:191], v[208:211], v[98:101]
	v_mfma_f32_16x16x32_bf16 v[98:101], v[184:187], v[204:207], v[98:101]
	v_mfma_f32_16x16x32_bf16 v[94:97], v[130:133], v[212:215], v[94:97]
	v_mfma_f32_16x16x32_bf16 v[94:97], v[134:137], v[220:223], v[94:97]
	v_mfma_f32_16x16x32_bf16 v[90:93], v[142:145], v[220:223], v[90:93]
	v_mfma_f32_16x16x32_bf16 v[90:93], v[138:141], v[212:215], v[90:93]
	v_mfma_f32_16x16x32_bf16 v[86:89], v[162:165], v[212:215], v[86:89]
	v_mfma_f32_16x16x32_bf16 v[86:89], v[180:183], v[220:223], v[86:89]
	v_mfma_f32_16x16x32_bf16 v[82:85], v[188:191], v[220:223], v[82:85]
	v_mfma_f32_16x16x32_bf16 v[82:85], v[184:187], v[212:215], v[82:85]
	v_mfma_f32_16x16x32_bf16 v[78:81], v[130:133], v[224:227], v[78:81]
	v_mfma_f32_16x16x32_bf16 v[78:81], v[134:137], v[228:231], v[78:81]
	v_mfma_f32_16x16x32_bf16 v[74:77], v[142:145], v[228:231], v[74:77]
	v_mfma_f32_16x16x32_bf16 v[74:77], v[138:141], v[224:227], v[74:77]
	v_mfma_f32_16x16x32_bf16 v[70:73], v[162:165], v[224:227], v[70:73]
	v_mfma_f32_16x16x32_bf16 v[70:73], v[180:183], v[228:231], v[70:73]
	v_mfma_f32_16x16x32_bf16 v[66:69], v[188:191], v[228:231], v[66:69]
	v_mfma_f32_16x16x32_bf16 v[66:69], v[184:187], v[224:227], v[66:69]
	s_setprio 0
	s_waitcnt vmcnt(8)
	s_barrier
	ds_read_b128 v[196:199], v179 offset:49152
	ds_read_b128 v[200:203], v179 offset:50176
	ds_read_b128 v[204:207], v179 offset:51200
	ds_read_b128 v[208:211], v179 offset:52224
	ds_read_b128 v[212:215], v179 offset:53248
	ds_read_b128 v[220:223], v179 offset:54272
	ds_read_b128 v[224:227], v179 offset:55296
	ds_read_b128 v[228:231], v179 offset:56320
	s_add_u32 s60, s40, 0x80
	s_addc_u32 s61, s41, 0
	s_add_u32 vcc_lo, s60, 0x100000
	s_addc_u32 vcc_hi, s61, 0
	s_add_i32 m0, s24, 0x18000
	s_nop 0
	global_load_lds_dwordx4 v148, s[60:61]
	s_add_i32 m0, s24, 0x1a000
	s_nop 0
	global_load_lds_dwordx4 v152, s[60:61]
	s_add_i32 m0, s24, 0x1c000
	s_nop 0
	global_load_lds_dwordx4 v148, vcc
	s_add_i32 m0, s24, 0x1e000
	s_nop 0
	global_load_lds_dwordx4 v152, vcc
	s_add_u32 s60, s42, 0x80
	s_addc_u32 s61, s43, 0
	s_add_i32 m0, s24, 0x8000
	s_nop 0
	global_load_lds_dwordx4 v146, s[60:61]
	s_add_i32 m0, s24, 0xa000
	s_nop 0
	global_load_lds_dwordx4 v150, s[60:61]
	s_waitcnt lgkmcnt(0)
	s_setprio 1
	v_mfma_f32_16x16x32_bf16 v[62:65], v[130:133], v[196:199], v[62:65]
	v_mfma_f32_16x16x32_bf16 v[62:65], v[134:137], v[200:203], v[62:65]
	v_mfma_f32_16x16x32_bf16 v[58:61], v[142:145], v[200:203], v[58:61]
	v_mfma_f32_16x16x32_bf16 v[58:61], v[138:141], v[196:199], v[58:61]
	v_mfma_f32_16x16x32_bf16 v[54:57], v[162:165], v[196:199], v[54:57]
	v_mfma_f32_16x16x32_bf16 v[54:57], v[180:183], v[200:203], v[54:57]
	v_mfma_f32_16x16x32_bf16 v[50:53], v[188:191], v[200:203], v[50:53]
	v_mfma_f32_16x16x32_bf16 v[50:53], v[184:187], v[196:199], v[50:53]
	v_mfma_f32_16x16x32_bf16 v[46:49], v[130:133], v[204:207], v[46:49]
	v_mfma_f32_16x16x32_bf16 v[46:49], v[134:137], v[208:211], v[46:49]
	v_mfma_f32_16x16x32_bf16 v[42:45], v[142:145], v[208:211], v[42:45]
	v_mfma_f32_16x16x32_bf16 v[42:45], v[138:141], v[204:207], v[42:45]
	v_mfma_f32_16x16x32_bf16 v[38:41], v[162:165], v[204:207], v[38:41]
	v_mfma_f32_16x16x32_bf16 v[38:41], v[180:183], v[208:211], v[38:41]
	v_mfma_f32_16x16x32_bf16 v[34:37], v[188:191], v[208:211], v[34:37]
	v_mfma_f32_16x16x32_bf16 v[34:37], v[184:187], v[204:207], v[34:37]
	v_mfma_f32_16x16x32_bf16 v[30:33], v[130:133], v[212:215], v[30:33]
	v_mfma_f32_16x16x32_bf16 v[30:33], v[134:137], v[220:223], v[30:33]
	v_mfma_f32_16x16x32_bf16 v[26:29], v[142:145], v[220:223], v[26:29]
	v_mfma_f32_16x16x32_bf16 v[26:29], v[138:141], v[212:215], v[26:29]
	v_mfma_f32_16x16x32_bf16 v[22:25], v[162:165], v[212:215], v[22:25]
	v_mfma_f32_16x16x32_bf16 v[22:25], v[180:183], v[220:223], v[22:25]
	v_mfma_f32_16x16x32_bf16 v[18:21], v[188:191], v[220:223], v[18:21]
	v_mfma_f32_16x16x32_bf16 v[18:21], v[184:187], v[212:215], v[18:21]
	v_mfma_f32_16x16x32_bf16 v[14:17], v[130:133], v[224:227], v[14:17]
	v_mfma_f32_16x16x32_bf16 v[14:17], v[134:137], v[228:231], v[14:17]
	v_mfma_f32_16x16x32_bf16 v[10:13], v[142:145], v[228:231], v[10:13]
	v_mfma_f32_16x16x32_bf16 v[10:13], v[138:141], v[224:227], v[10:13]
	v_mfma_f32_16x16x32_bf16 v[6:9], v[162:165], v[224:227], v[6:9]
	v_mfma_f32_16x16x32_bf16 v[6:9], v[180:183], v[228:231], v[6:9]
	v_mfma_f32_16x16x32_bf16 v[2:5], v[188:191], v[228:231], v[2:5]
	v_mfma_f32_16x16x32_bf16 v[2:5], v[184:187], v[224:227], v[2:5]
	s_setprio 0
	s_waitcnt vmcnt(8)
	s_barrier
	s_add_i32 s58, s58, 2
	s_add_u32 s36, s36, 0x100
	s_addc_u32 s37, s37, 0
	s_add_u32 s56, s56, 0x100
	s_addc_u32 s57, s57, 0
	s_cmp_gt_u32 s58, 61
	s_cbranch_scc0 .LBB0_1251
	s_branch .Lf1_exit
; #define PG8_STAGE(bufoff, gbase, voff) do { _Pragma("unroll") for (int _i = 0; _i < 2; ++_i) \
;         __builtin_amdgcn_global_load_lds((const unsigned*)((const char*)(gbase) + (voff)[_i]), (PG8_LAS unsigned*)(lds + (bufoff) + ldsw + _i * 8192), 16, 0, 0); } while (0)
; #define PG8_LDA(dst, b, h) do { _Pragma("unroll") for (int m = 0; m < 4; ++m) _Pragma("unroll") for (int k = 0; k < 2; ++k) dst[m][k] = *(const PG8_LAS bf16x8*)(lds + PG8_SA(b, h) + aoff + m * 2048 + k * 1024); } while (0)
; #define PG8_LDB(dst, b, h) do { _Pragma("unroll") for (int n = 0; n < 2; ++n) _Pragma("unroll") for (int k = 0; k < 2; ++k) dst[n][k] = *(const PG8_LAS bf16x8*)(lds + PG8_SB(b, h) + boff + n * 2048 + k * 1024); } while (0)
; #define PG8_MMA(ai, bj, At, Bt) do { __builtin_amdgcn_s_setprio(1); _Pragma("unroll") for (int m = 0; m < 4; ++m) _Pragma("unroll") for (int n = 0; n < 2; ++n) _Pragma("unroll") for (int k = 0; k < 2; ++k) \
;         acc[ai][bj][m][n] = __builtin_amdgcn_mfma_f32_16x16x32_bf16(Bt[n][k], At[m][k], acc[ai][bj][m][n], 0, 0, 0); __builtin_amdgcn_s_setprio(0); } while (0)
; #define PG8_WAIT_V(n) asm volatile("s_waitcnt vmcnt(" #n ")" ::: "memory")
; #define PG8_WAIT_L(n) asm volatile("s_waitcnt lgkmcnt(" #n ")" ::: "memory")
; #define PG8_BAR __builtin_amdgcn_s_barrier()
; #define PG8_SCHED __builtin_amdgcn_sched_barrier(0)
; template <class Epi, class Sched, bool ALIGN_EPI = false, bool SP2 = false>
; __device__ __forceinline__ void gemm_phase(PG8_LAS unsigned char* lds, const Gemm g, const Sched& S, const Epi& E) {
;     ...
;             PG8_LDB(B0, 0, 0); PG8_LDB(B1, 0, 1); PG8_SCHED; PG8_LDA(At, 0, 0); PG8_STAGE(PG8_SA(1, 1), a1 + hstep, voffA);
;             PG8_WAIT_V(8); PG8_WAIT_L(0); PG8_BAR; PG8_MMA(0, 0, At, B0); PG8_MMA(0, 1, At, B1); PG8_BAR; PG8_SCHED;
;             PG8_LDA(At, 0, 1); PG8_STAGE(PG8_SB(0, 0), b2, voffB); PG8_STAGE(PG8_SB(0, 1), b2 + hstep, voffB); PG8_STAGE(PG8_SA(0, 0), a2, voffA);
;             PG8_WAIT_V(8); PG8_WAIT_L(0); PG8_BAR; PG8_MMA(1, 0, At, B0); PG8_MMA(1, 1, At, B1); PG8_BAR; PG8_SCHED;
.Lf1_h1:
	ds_read_b128 v[130:133], v177
	ds_read_b128 v[134:137], v177 offset:1024
	ds_read_b128 v[138:141], v177 offset:2048
	ds_read_b128 v[142:145], v177 offset:3072
	ds_read_b128 v[162:165], v178
	ds_read_b128 v[180:183], v178 offset:1024
	ds_read_b128 v[184:187], v178 offset:2048
	ds_read_b128 v[188:191], v178 offset:3072
	s_add_u32 s40, s36, 0xfff00080
	s_addc_u32 s41, s37, -1
	s_cmp_eq_u32 s58, 60
	s_cselect_b32 s43, s15, s41
	s_cselect_b32 s42, s17, s40
	s_cselect_b32 s41, s54, s57
	s_cselect_b32 s40, s55, s56
	ds_read_b128 v[196:199], v179
	ds_read_b128 v[200:203], v179 offset:1024
	ds_read_b128 v[204:207], v179 offset:2048
	ds_read_b128 v[208:211], v179 offset:3072
	ds_read_b128 v[212:215], v179 offset:4096
	ds_read_b128 v[220:223], v179 offset:5120
	ds_read_b128 v[224:227], v179 offset:6144
	ds_read_b128 v[228:231], v179 offset:7168
	s_add_i32 m0, s24, 0xc000
	s_nop 0
	global_load_lds_dwordx4 v146, s[36:37]
	s_add_i32 m0, s24, 0xe000
	s_nop 0
	global_load_lds_dwordx4 v150, s[36:37]
	s_sleep 2
	s_waitcnt lgkmcnt(0)
	s_waitcnt vmcnt(8)
	s_barrier
	s_setprio 2
	v_mfma_f32_16x16x32_bf16 v[126:129], v[130:133], v[196:199], v[126:129]
	v_mfma_f32_16x16x32_bf16 v[126:129], v[134:137], v[200:203], v[126:129]
	v_mfma_f32_16x16x32_bf16 v[122:125], v[142:145], v[200:203], v[122:125]
	v_mfma_f32_16x16x32_bf16 v[122:125], v[138:141], v[196:199], v[122:125]
	v_mfma_f32_16x16x32_bf16 v[118:121], v[162:165], v[196:199], v[118:121]
	v_mfma_f32_16x16x32_bf16 v[118:121], v[180:183], v[200:203], v[118:121]
	v_mfma_f32_16x16x32_bf16 v[114:117], v[188:191], v[200:203], v[114:117]
	v_mfma_f32_16x16x32_bf16 v[114:117], v[184:187], v[196:199], v[114:117]
	v_mfma_f32_16x16x32_bf16 v[110:113], v[130:133], v[204:207], v[110:113]
	v_mfma_f32_16x16x32_bf16 v[110:113], v[134:137], v[208:211], v[110:113]
	v_mfma_f32_16x16x32_bf16 v[106:109], v[142:145], v[208:211], v[106:109]
	v_mfma_f32_16x16x32_bf16 v[106:109], v[138:141], v[204:207], v[106:109]
	v_mfma_f32_16x16x32_bf16 v[102:105], v[162:165], v[204:207], v[102:105]
	v_mfma_f32_16x16x32_bf16 v[102:105], v[180:183], v[208:211], v[102:105]
	v_mfma_f32_16x16x32_bf16 v[98:101], v[188:191], v[208:211], v[98:101]
	v_mfma_f32_16x16x32_bf16 v[98:101], v[184:187], v[204:207], v[98:101]
	v_mfma_f32_16x16x32_bf16 v[94:97], v[130:133], v[212:215], v[94:97]
	v_mfma_f32_16x16x32_bf16 v[94:97], v[134:137], v[220:223], v[94:97]
	v_mfma_f32_16x16x32_bf16 v[90:93], v[142:145], v[220:223], v[90:93]
	v_mfma_f32_16x16x32_bf16 v[90:93], v[138:141], v[212:215], v[90:93]
	v_mfma_f32_16x16x32_bf16 v[86:89], v[162:165], v[212:215], v[86:89]
	v_mfma_f32_16x16x32_bf16 v[86:89], v[180:183], v[220:223], v[86:89]
	v_mfma_f32_16x16x32_bf16 v[82:85], v[188:191], v[220:223], v[82:85]
	v_mfma_f32_16x16x32_bf16 v[82:85], v[184:187], v[212:215], v[82:85]
	v_mfma_f32_16x16x32_bf16 v[78:81], v[130:133], v[224:227], v[78:81]
	v_mfma_f32_16x16x32_bf16 v[78:81], v[134:137], v[228:231], v[78:81]
	v_mfma_f32_16x16x32_bf16 v[74:77], v[142:145], v[228:231], v[74:77]
	v_mfma_f32_16x16x32_bf16 v[74:77], v[138:141], v[224:227], v[74:77]
	v_mfma_f32_16x16x32_bf16 v[70:73], v[162:165], v[224:227], v[70:73]
	v_mfma_f32_16x16x32_bf16 v[70:73], v[180:183], v[228:231], v[70:73]
	v_mfma_f32_16x16x32_bf16 v[66:69], v[188:191], v[228:231], v[66:69]
	v_mfma_f32_16x16x32_bf16 v[66:69], v[184:187], v[224:227], v[66:69]
	s_setprio 0
	ds_read_b128 v[196:199], v179 offset:16384
	ds_read_b128 v[200:203], v179 offset:17408
	ds_read_b128 v[204:207], v179 offset:18432
	ds_read_b128 v[208:211], v179 offset:19456
	ds_read_b128 v[212:215], v179 offset:20480
	ds_read_b128 v[220:223], v179 offset:21504
	ds_read_b128 v[224:227], v179 offset:22528
	ds_read_b128 v[228:231], v179 offset:23552
	s_add_u32 vcc_lo, s40, 0x100000
	s_addc_u32 vcc_hi, s41, 0
	s_add_i32 m0, s24, 0x10000
	s_nop 0
	global_load_lds_dwordx4 v148, s[40:41]
	s_add_i32 m0, s24, 0x12000
	s_nop 0
	global_load_lds_dwordx4 v152, s[40:41]
	s_add_i32 m0, s24, 0x14000
	s_nop 0
	global_load_lds_dwordx4 v148, vcc
	s_add_i32 m0, s24, 0x16000
	s_nop 0
	global_load_lds_dwordx4 v152, vcc
	s_mov_b32 m0, s24
	s_nop 0
	global_load_lds_dwordx4 v146, s[42:43]
	s_add_i32 m0, s24, 0x2000
	s_nop 0
	global_load_lds_dwordx4 v150, s[42:43]
	s_sleep 2
	s_waitcnt lgkmcnt(0)
	s_waitcnt vmcnt(8)
	s_barrier
; #define PG8_STAGE(bufoff, gbase, voff) do { _Pragma("unroll") for (int _i = 0; _i < 2; ++_i) \
;         __builtin_amdgcn_global_load_lds((const unsigned*)((const char*)(gbase) + (voff)[_i]), (PG8_LAS unsigned*)(lds + (bufoff) + ldsw + _i * 8192), 16, 0, 0); } while (0)
; #define PG8_LDA(dst, b, h) do { _Pragma("unroll") for (int m = 0; m < 4; ++m) _Pragma("unroll") for (int k = 0; k < 2; ++k) dst[m][k] = *(const PG8_LAS bf16x8*)(lds + PG8_SA(b, h) + aoff + m * 2048 + k * 1024); } while (0)
; #define PG8_LDB(dst, b, h) do { _Pragma("unroll") for (int n = 0; n < 2; ++n) _Pragma("unroll") for (int k = 0; k < 2; ++k) dst[n][k] = *(const PG8_LAS bf16x8*)(lds + PG8_SB(b, h) + boff + n * 2048 + k * 1024); } while (0)
; #define PG8_MMA(ai, bj, At, Bt) do { __builtin_amdgcn_s_setprio(1); _Pragma("unroll") for (int m = 0; m < 4; ++m) _Pragma("unroll") for (int n = 0; n < 2; ++n) _Pragma("unroll") for (int k = 0; k < 2; ++k) \
;         acc[ai][bj][m][n] = __builtin_amdgcn_mfma_f32_16x16x32_bf16(Bt[n][k], At[m][k], acc[ai][bj][m][n], 0, 0, 0); __builtin_amdgcn_s_setprio(0); } while (0)
; #define PG8_WAIT_V(n) asm volatile("s_waitcnt vmcnt(" #n ")" ::: "memory")
; #define PG8_WAIT_L(n) asm volatile("s_waitcnt lgkmcnt(" #n ")" ::: "memory")
; #define PG8_BAR __builtin_amdgcn_s_barrier()
; #define PG8_SCHED __builtin_amdgcn_sched_barrier(0)
; template <class Epi, class Sched, bool ALIGN_EPI = false, bool SP2 = false>
; __device__ __forceinline__ void gemm_phase(PG8_LAS unsigned char* lds, const Gemm g, const Sched& S, const Epi& E) {
;     ...
;             PG8_WAIT_V(8); PG8_WAIT_L(0); PG8_BAR; PG8_MMA(1, 0, At, B0); PG8_MMA(1, 1, At, B1); PG8_BAR; PG8_SCHED;
;             PG8_LDB(B0, 1, 0); PG8_LDB(B1, 1, 1); PG8_SCHED; PG8_LDA(At, 1, 0); PG8_STAGE(PG8_SA(0, 1), a2 + hstep, voffA);
;             PG8_WAIT_V(8); PG8_WAIT_L(0); PG8_BAR; PG8_MMA(0, 0, At, B0); PG8_MMA(0, 1, At, B1); PG8_BAR; PG8_SCHED;
	s_setprio 2
	v_mfma_f32_16x16x32_bf16 v[62:65], v[130:133], v[196:199], v[62:65]
	v_mfma_f32_16x16x32_bf16 v[62:65], v[134:137], v[200:203], v[62:65]
	v_mfma_f32_16x16x32_bf16 v[58:61], v[142:145], v[200:203], v[58:61]
	v_mfma_f32_16x16x32_bf16 v[58:61], v[138:141], v[196:199], v[58:61]
	v_mfma_f32_16x16x32_bf16 v[54:57], v[162:165], v[196:199], v[54:57]
	v_mfma_f32_16x16x32_bf16 v[54:57], v[180:183], v[200:203], v[54:57]
	v_mfma_f32_16x16x32_bf16 v[50:53], v[188:191], v[200:203], v[50:53]
	v_mfma_f32_16x16x32_bf16 v[50:53], v[184:187], v[196:199], v[50:53]
	v_mfma_f32_16x16x32_bf16 v[46:49], v[130:133], v[204:207], v[46:49]
	v_mfma_f32_16x16x32_bf16 v[46:49], v[134:137], v[208:211], v[46:49]
	v_mfma_f32_16x16x32_bf16 v[42:45], v[142:145], v[208:211], v[42:45]
	v_mfma_f32_16x16x32_bf16 v[42:45], v[138:141], v[204:207], v[42:45]
	v_mfma_f32_16x16x32_bf16 v[38:41], v[162:165], v[204:207], v[38:41]
	v_mfma_f32_16x16x32_bf16 v[38:41], v[180:183], v[208:211], v[38:41]
	v_mfma_f32_16x16x32_bf16 v[34:37], v[188:191], v[208:211], v[34:37]
	v_mfma_f32_16x16x32_bf16 v[34:37], v[184:187], v[204:207], v[34:37]
	v_mfma_f32_16x16x32_bf16 v[30:33], v[130:133], v[212:215], v[30:33]
	v_mfma_f32_16x16x32_bf16 v[30:33], v[134:137], v[220:223], v[30:33]
	v_mfma_f32_16x16x32_bf16 v[26:29], v[142:145], v[220:223], v[26:29]
	v_mfma_f32_16x16x32_bf16 v[26:29], v[138:141], v[212:215], v[26:29]
	v_mfma_f32_16x16x32_bf16 v[22:25], v[162:165], v[212:215], v[22:25]
	v_mfma_f32_16x16x32_bf16 v[22:25], v[180:183], v[220:223], v[22:25]
	v_mfma_f32_16x16x32_bf16 v[18:21], v[188:191], v[220:223], v[18:21]
	v_mfma_f32_16x16x32_bf16 v[18:21], v[184:187], v[212:215], v[18:21]
	v_mfma_f32_16x16x32_bf16 v[14:17], v[130:133], v[224:227], v[14:17]
	v_mfma_f32_16x16x32_bf16 v[14:17], v[134:137], v[228:231], v[14:17]
	v_mfma_f32_16x16x32_bf16 v[10:13], v[142:145], v[228:231], v[10:13]
	v_mfma_f32_16x16x32_bf16 v[10:13], v[138:141], v[224:227], v[10:13]
	v_mfma_f32_16x16x32_bf16 v[6:9], v[162:165], v[224:227], v[6:9]
	v_mfma_f32_16x16x32_bf16 v[6:9], v[180:183], v[228:231], v[6:9]
	v_mfma_f32_16x16x32_bf16 v[2:5], v[188:191], v[228:231], v[2:5]
	v_mfma_f32_16x16x32_bf16 v[2:5], v[184:187], v[224:227], v[2:5]
	s_setprio 0
	s_add_i32 s59, 0, 0x18000
	s_add_i32 s60, 0, 0x1c000
	v_add_u32_e32 v142, s59, v166
	v_add_u32_e32 v188, s60, v166
	ds_read_b128 v[130:133], v142
	ds_read_b128 v[134:137], v142 offset:1024
	ds_read_b128 v[138:141], v142 offset:2048
	ds_read_b128 v[142:145], v142 offset:3072
	ds_read_b128 v[162:165], v188
	ds_read_b128 v[180:183], v188 offset:1024
	ds_read_b128 v[184:187], v188 offset:2048
	ds_read_b128 v[188:191], v188 offset:3072
	ds_read_b128 v[196:199], v179 offset:32768
	ds_read_b128 v[200:203], v179 offset:33792
	ds_read_b128 v[204:207], v179 offset:34816
	ds_read_b128 v[208:211], v179 offset:35840
	ds_read_b128 v[212:215], v179 offset:36864
	ds_read_b128 v[220:223], v179 offset:37888
	ds_read_b128 v[224:227], v179 offset:38912
	ds_read_b128 v[228:231], v179 offset:39936
	s_add_u32 vcc_lo, s42, 0x100000
	s_addc_u32 vcc_hi, s43, 0
	s_add_i32 m0, s24, 0x4000
	s_nop 0
	global_load_lds_dwordx4 v146, vcc
	s_add_i32 m0, s24, 0x6000
	s_nop 0
	global_load_lds_dwordx4 v150, vcc
	s_sleep 2
	s_waitcnt lgkmcnt(0)
	s_waitcnt vmcnt(8)
	s_barrier
; #define PG8_STAGE(bufoff, gbase, voff) do { _Pragma("unroll") for (int _i = 0; _i < 2; ++_i) \
;         __builtin_amdgcn_global_load_lds((const unsigned*)((const char*)(gbase) + (voff)[_i]), (PG8_LAS unsigned*)(lds + (bufoff) + ldsw + _i * 8192), 16, 0, 0); } while (0)
; #define PG8_LDA(dst, b, h) do { _Pragma("unroll") for (int m = 0; m < 4; ++m) _Pragma("unroll") for (int k = 0; k < 2; ++k) dst[m][k] = *(const PG8_LAS bf16x8*)(lds + PG8_SA(b, h) + aoff + m * 2048 + k * 1024); } while (0)
; #define PG8_MMA(ai, bj, At, Bt) do { __builtin_amdgcn_s_setprio(1); _Pragma("unroll") for (int m = 0; m < 4; ++m) _Pragma("unroll") for (int n = 0; n < 2; ++n) _Pragma("unroll") for (int k = 0; k < 2; ++k) \
;         acc[ai][bj][m][n] = __builtin_amdgcn_mfma_f32_16x16x32_bf16(Bt[n][k], At[m][k], acc[ai][bj][m][n], 0, 0, 0); __builtin_amdgcn_s_setprio(0); } while (0)
; #define PG8_WAIT_V(n) asm volatile("s_waitcnt vmcnt(" #n ")" ::: "memory")
; #define PG8_WAIT_L(n) asm volatile("s_waitcnt lgkmcnt(" #n ")" ::: "memory")
; #define PG8_BAR __builtin_amdgcn_s_barrier()
; #define PG8_SCHED __builtin_amdgcn_sched_barrier(0)
; template <class Epi, class Sched, bool ALIGN_EPI = false, bool SP2 = false>
; __device__ __forceinline__ void gemm_phase(PG8_LAS unsigned char* lds, const Gemm g, const Sched& S, const Epi& E) {
;     ...
;             PG8_WAIT_V(8); PG8_WAIT_L(0); PG8_BAR; PG8_MMA(0, 0, At, B0); PG8_MMA(0, 1, At, B1); PG8_BAR; PG8_SCHED;
;             PG8_LDA(At, 1, 1); PG8_STAGE(PG8_SB(1, 0), b3, voffB); PG8_STAGE(PG8_SB(1, 1), b3 + hstep, voffB); PG8_STAGE(PG8_SA(1, 0), a3, voffA);
;             PG8_WAIT_V(8); PG8_WAIT_L(0); PG8_BAR; PG8_MMA(1, 0, At, B0); PG8_MMA(1, 1, At, B1); PG8_BAR; PG8_SCHED;
	s_setprio 2
	v_mfma_f32_16x16x32_bf16 v[126:129], v[130:133], v[196:199], v[126:129]
	v_mfma_f32_16x16x32_bf16 v[126:129], v[134:137], v[200:203], v[126:129]
	v_mfma_f32_16x16x32_bf16 v[122:125], v[142:145], v[200:203], v[122:125]
	v_mfma_f32_16x16x32_bf16 v[122:125], v[138:141], v[196:199], v[122:125]
	v_mfma_f32_16x16x32_bf16 v[118:121], v[162:165], v[196:199], v[118:121]
	v_mfma_f32_16x16x32_bf16 v[118:121], v[180:183], v[200:203], v[118:121]
	v_mfma_f32_16x16x32_bf16 v[114:117], v[188:191], v[200:203], v[114:117]
	v_mfma_f32_16x16x32_bf16 v[114:117], v[184:187], v[196:199], v[114:117]
	v_mfma_f32_16x16x32_bf16 v[110:113], v[130:133], v[204:207], v[110:113]
	v_mfma_f32_16x16x32_bf16 v[110:113], v[134:137], v[208:211], v[110:113]
	v_mfma_f32_16x16x32_bf16 v[106:109], v[142:145], v[208:211], v[106:109]
	v_mfma_f32_16x16x32_bf16 v[106:109], v[138:141], v[204:207], v[106:109]
	v_mfma_f32_16x16x32_bf16 v[102:105], v[162:165], v[204:207], v[102:105]
	v_mfma_f32_16x16x32_bf16 v[102:105], v[180:183], v[208:211], v[102:105]
	v_mfma_f32_16x16x32_bf16 v[98:101], v[188:191], v[208:211], v[98:101]
	v_mfma_f32_16x16x32_bf16 v[98:101], v[184:187], v[204:207], v[98:101]
	v_mfma_f32_16x16x32_bf16 v[94:97], v[130:133], v[212:215], v[94:97]
	v_mfma_f32_16x16x32_bf16 v[94:97], v[134:137], v[220:223], v[94:97]
	v_mfma_f32_16x16x32_bf16 v[90:93], v[142:145], v[220:223], v[90:93]
	v_mfma_f32_16x16x32_bf16 v[90:93], v[138:141], v[212:215], v[90:93]
	v_mfma_f32_16x16x32_bf16 v[86:89], v[162:165], v[212:215], v[86:89]
	v_mfma_f32_16x16x32_bf16 v[86:89], v[180:183], v[220:223], v[86:89]
	v_mfma_f32_16x16x32_bf16 v[82:85], v[188:191], v[220:223], v[82:85]
	v_mfma_f32_16x16x32_bf16 v[82:85], v[184:187], v[212:215], v[82:85]
	v_mfma_f32_16x16x32_bf16 v[78:81], v[130:133], v[224:227], v[78:81]
	v_mfma_f32_16x16x32_bf16 v[78:81], v[134:137], v[228:231], v[78:81]
	v_mfma_f32_16x16x32_bf16 v[74:77], v[142:145], v[228:231], v[74:77]
	v_mfma_f32_16x16x32_bf16 v[74:77], v[138:141], v[224:227], v[74:77]
	v_mfma_f32_16x16x32_bf16 v[70:73], v[162:165], v[224:227], v[70:73]
	v_mfma_f32_16x16x32_bf16 v[70:73], v[180:183], v[228:231], v[70:73]
	v_mfma_f32_16x16x32_bf16 v[66:69], v[188:191], v[228:231], v[66:69]
	v_mfma_f32_16x16x32_bf16 v[66:69], v[184:187], v[224:227], v[66:69]
	s_setprio 0
	ds_read_b128 v[196:199], v179 offset:49152
	ds_read_b128 v[200:203], v179 offset:50176
	ds_read_b128 v[204:207], v179 offset:51200
	ds_read_b128 v[208:211], v179 offset:52224
	ds_read_b128 v[212:215], v179 offset:53248
	ds_read_b128 v[220:223], v179 offset:54272
	ds_read_b128 v[224:227], v179 offset:55296
	ds_read_b128 v[228:231], v179 offset:56320
	s_add_u32 s60, s40, 0x80
	s_addc_u32 s61, s41, 0
	s_add_u32 vcc_lo, s60, 0x100000
	s_addc_u32 vcc_hi, s61, 0
	s_add_i32 m0, s24, 0x18000
	s_nop 0
	global_load_lds_dwordx4 v148, s[60:61]
	s_add_i32 m0, s24, 0x1a000
	s_nop 0
	global_load_lds_dwordx4 v152, s[60:61]
	s_add_i32 m0, s24, 0x1c000
	s_nop 0
	global_load_lds_dwordx4 v148, vcc
	s_add_i32 m0, s24, 0x1e000
	s_nop 0
	global_load_lds_dwordx4 v152, vcc
	s_add_u32 s60, s42, 0x80
	s_addc_u32 s61, s43, 0
	s_add_i32 m0, s24, 0x8000
	s_nop 0
	global_load_lds_dwordx4 v146, s[60:61]
	s_add_i32 m0, s24, 0xa000
	s_nop 0
	global_load_lds_dwordx4 v150, s[60:61]
	s_sleep 2
	s_waitcnt lgkmcnt(0)
	s_waitcnt vmcnt(8)
	s_barrier
	s_setprio 2
	v_mfma_f32_16x16x32_bf16 v[62:65], v[130:133], v[196:199], v[62:65]
	v_mfma_f32_16x16x32_bf16 v[62:65], v[134:137], v[200:203], v[62:65]
	v_mfma_f32_16x16x32_bf16 v[58:61], v[142:145], v[200:203], v[58:61]
	v_mfma_f32_16x16x32_bf16 v[58:61], v[138:141], v[196:199], v[58:61]
	v_mfma_f32_16x16x32_bf16 v[54:57], v[162:165], v[196:199], v[54:57]
	v_mfma_f32_16x16x32_bf16 v[54:57], v[180:183], v[200:203], v[54:57]
	v_mfma_f32_16x16x32_bf16 v[50:53], v[188:191], v[200:203], v[50:53]
	v_mfma_f32_16x16x32_bf16 v[50:53], v[184:187], v[196:199], v[50:53]
	v_mfma_f32_16x16x32_bf16 v[46:49], v[130:133], v[204:207], v[46:49]
	v_mfma_f32_16x16x32_bf16 v[46:49], v[134:137], v[208:211], v[46:49]
	v_mfma_f32_16x16x32_bf16 v[42:45], v[142:145], v[208:211], v[42:45]
	v_mfma_f32_16x16x32_bf16 v[42:45], v[138:141], v[204:207], v[42:45]
	v_mfma_f32_16x16x32_bf16 v[38:41], v[162:165], v[204:207], v[38:41]
	v_mfma_f32_16x16x32_bf16 v[38:41], v[180:183], v[208:211], v[38:41]
	v_mfma_f32_16x16x32_bf16 v[34:37], v[188:191], v[208:211], v[34:37]
	v_mfma_f32_16x16x32_bf16 v[34:37], v[184:187], v[204:207], v[34:37]
	v_mfma_f32_16x16x32_bf16 v[30:33], v[130:133], v[212:215], v[30:33]
	v_mfma_f32_16x16x32_bf16 v[30:33], v[134:137], v[220:223], v[30:33]
	v_mfma_f32_16x16x32_bf16 v[26:29], v[142:145], v[220:223], v[26:29]
	v_mfma_f32_16x16x32_bf16 v[26:29], v[138:141], v[212:215], v[26:29]
	v_mfma_f32_16x16x32_bf16 v[22:25], v[162:165], v[212:215], v[22:25]
	v_mfma_f32_16x16x32_bf16 v[22:25], v[180:183], v[220:223], v[22:25]
	v_mfma_f32_16x16x32_bf16 v[18:21], v[188:191], v[220:223], v[18:21]
	v_mfma_f32_16x16x32_bf16 v[18:21], v[184:187], v[212:215], v[18:21]
	v_mfma_f32_16x16x32_bf16 v[14:17], v[130:133], v[224:227], v[14:17]
	v_mfma_f32_16x16x32_bf16 v[14:17], v[134:137], v[228:231], v[14:17]
	v_mfma_f32_16x16x32_bf16 v[10:13], v[142:145], v[228:231], v[10:13]
	v_mfma_f32_16x16x32_bf16 v[10:13], v[138:141], v[224:227], v[10:13]
	v_mfma_f32_16x16x32_bf16 v[6:9], v[162:165], v[224:227], v[6:9]
	v_mfma_f32_16x16x32_bf16 v[6:9], v[180:183], v[228:231], v[6:9]
	v_mfma_f32_16x16x32_bf16 v[2:5], v[188:191], v[228:231], v[2:5]
	v_mfma_f32_16x16x32_bf16 v[2:5], v[184:187], v[224:227], v[2:5]
	s_setprio 0
	s_add_i32 s58, s58, 2
	s_add_u32 s36, s36, 0x100
	s_addc_u32 s37, s37, 0
	s_add_u32 s56, s56, 0x100
	s_addc_u32 s57, s57, 0
	s_cmp_gt_u32 s58, 61
	s_cbranch_scc0 .Lf1_h1

; #define PG8_STAGE(bufoff, gbase, voff) do { _Pragma("unroll") for (int _i = 0; _i < 2; ++_i) \
;         __builtin_amdgcn_global_load_lds((const unsigned*)((const char*)(gbase) + (voff)[_i]), (PG8_LAS unsigned*)(lds + (bufoff) + ldsw + _i * 8192), 16, 0, 0); } while (0)
; #define PG8_LDA(dst, b, h) do { _Pragma("unroll") for (int m = 0; m < 4; ++m) _Pragma("unroll") for (int k = 0; k < 2; ++k) dst[m][k] = *(const PG8_LAS bf16x8*)(lds + PG8_SA(b, h) + aoff + m * 2048 + k * 1024); } while (0)
; #define PG8_LDB(dst, b, h) do { _Pragma("unroll") for (int n = 0; n < 2; ++n) _Pragma("unroll") for (int k = 0; k < 2; ++k) dst[n][k] = *(const PG8_LAS bf16x8*)(lds + PG8_SB(b, h) + boff + n * 2048 + k * 1024); } while (0)
; #define PG8_MMA(ai, bj, At, Bt) do { __builtin_amdgcn_s_setprio(1); _Pragma("unroll") for (int m = 0; m < 4; ++m) _Pragma("unroll") for (int n = 0; n < 2; ++n) _Pragma("unroll") for (int k = 0; k < 2; ++k) \
;         acc[ai][bj][m][n] = __builtin_amdgcn_mfma_f32_16x16x32_bf16(Bt[n][k], At[m][k], acc[ai][bj][m][n], 0, 0, 0); __builtin_amdgcn_s_setprio(0); } while (0)
; #define PG8_WAIT_V(n) asm volatile("s_waitcnt vmcnt(" #n ")" ::: "memory")
; #define PG8_WAIT_L(n) asm volatile("s_waitcnt lgkmcnt(" #n ")" ::: "memory")
; #define PG8_BAR __builtin_amdgcn_s_barrier()
; #define PG8_SCHED __builtin_amdgcn_sched_barrier(0)
; template <class Epi, class Sched, bool ALIGN_EPI = false, bool SP2 = false>
; __device__ __forceinline__ void gemm_phase(PG8_LAS unsigned char* lds, const Gemm g, const Sched& S, const Epi& E) {
;     ...
;             PG8_LDB(B0, 0, 0); PG8_LDB(B1, 0, 1); PG8_SCHED; PG8_LDA(At, 0, 0); PG8_STAGE(PG8_SA(1, 1), a1 + hstep, voffA);
;             PG8_WAIT_V(8); PG8_WAIT_L(0); PG8_BAR; PG8_MMA(0, 0, At, B0); PG8_MMA(0, 1, At, B1); PG8_BAR; PG8_SCHED;
;             PG8_LDA(At, 0, 1); PG8_STAGE(PG8_SB(0, 0), b2, voffB); PG8_STAGE(PG8_SB(0, 1), b2 + hstep, voffB); PG8_STAGE(PG8_SA(0, 0), a2, voffA);
;             PG8_WAIT_V(8); PG8_WAIT_L(0); PG8_BAR; PG8_MMA(1, 0, At, B0); PG8_MMA(1, 1, At, B1); PG8_BAR; PG8_SCHED;
.LBB0_1321:
	ds_read_b128 v[128:131], v156
	ds_read_b128 v[132:135], v156 offset:1024
	ds_read_b128 v[150:153], v156 offset:2048
	ds_read_b128 v[162:165], v156 offset:3072
	ds_read_b128 v[166:169], v157
	ds_read_b128 v[170:173], v157 offset:1024
	ds_read_b128 v[174:177], v157 offset:2048
	ds_read_b128 v[178:181], v157 offset:3072
	s_add_u32 s20, s18, 0xffbfc080
	s_addc_u32 s21, s19, -1
	s_cmpk_eq_i32 s59, 0xfc
	s_cselect_b32 s23, s7, s21
	s_cselect_b32 s22, s6, s20
	s_cselect_b32 s21, s17, s58
	s_cselect_b32 s20, s16, s57
	ds_read_b128 v[182:185], v158
	ds_read_b128 v[186:189], v158 offset:1024
	ds_read_b128 v[190:193], v158 offset:2048
	ds_read_b128 v[194:197], v158 offset:3072
	ds_read_b128 v[198:201], v158 offset:4096
	ds_read_b128 v[202:205], v158 offset:5120
	ds_read_b128 v[206:209], v158 offset:6144
	ds_read_b128 v[210:213], v158 offset:7168
	s_add_i32 m0, s24, 0xc000
	s_nop 0
	global_load_lds_dwordx4 v136, s[18:19]
	s_add_i32 m0, s24, 0xe000
	s_nop 0
	global_load_lds_dwordx4 v140, s[18:19]
	s_waitcnt lgkmcnt(0)
	s_setprio 1
	v_mfma_f32_16x16x32_bf16 v[124:127], v[128:131], v[182:185], v[124:127]
	v_mfma_f32_16x16x32_bf16 v[124:127], v[132:135], v[186:189], v[124:127]
	v_mfma_f32_16x16x32_bf16 v[120:123], v[162:165], v[186:189], v[120:123]
	v_mfma_f32_16x16x32_bf16 v[120:123], v[150:153], v[182:185], v[120:123]
	v_mfma_f32_16x16x32_bf16 v[68:71], v[166:169], v[182:185], v[68:71]
	v_mfma_f32_16x16x32_bf16 v[68:71], v[170:173], v[186:189], v[68:71]
	v_mfma_f32_16x16x32_bf16 v[64:67], v[178:181], v[186:189], v[64:67]
	v_mfma_f32_16x16x32_bf16 v[64:67], v[174:177], v[182:185], v[64:67]
	v_mfma_f32_16x16x32_bf16 v[116:119], v[128:131], v[190:193], v[116:119]
	v_mfma_f32_16x16x32_bf16 v[116:119], v[132:135], v[194:197], v[116:119]
	v_mfma_f32_16x16x32_bf16 v[112:115], v[162:165], v[194:197], v[112:115]
	v_mfma_f32_16x16x32_bf16 v[112:115], v[150:153], v[190:193], v[112:115]
	v_mfma_f32_16x16x32_bf16 v[52:55], v[166:169], v[190:193], v[52:55]
	v_mfma_f32_16x16x32_bf16 v[52:55], v[170:173], v[194:197], v[52:55]
	v_mfma_f32_16x16x32_bf16 v[48:51], v[178:181], v[194:197], v[48:51]
	v_mfma_f32_16x16x32_bf16 v[48:51], v[174:177], v[190:193], v[48:51]
	v_mfma_f32_16x16x32_bf16 v[108:111], v[128:131], v[198:201], v[108:111]
	v_mfma_f32_16x16x32_bf16 v[108:111], v[132:135], v[202:205], v[108:111]
	v_mfma_f32_16x16x32_bf16 v[104:107], v[162:165], v[202:205], v[104:107]
	v_mfma_f32_16x16x32_bf16 v[104:107], v[150:153], v[198:201], v[104:107]
	v_mfma_f32_16x16x32_bf16 v[44:47], v[166:169], v[198:201], v[44:47]
	v_mfma_f32_16x16x32_bf16 v[44:47], v[170:173], v[202:205], v[44:47]
	v_mfma_f32_16x16x32_bf16 v[40:43], v[178:181], v[202:205], v[40:43]
	v_mfma_f32_16x16x32_bf16 v[40:43], v[174:177], v[198:201], v[40:43]
	v_mfma_f32_16x16x32_bf16 v[100:103], v[128:131], v[206:209], v[100:103]
	v_mfma_f32_16x16x32_bf16 v[100:103], v[132:135], v[210:213], v[100:103]
	v_mfma_f32_16x16x32_bf16 v[96:99], v[162:165], v[210:213], v[96:99]
	v_mfma_f32_16x16x32_bf16 v[96:99], v[150:153], v[206:209], v[96:99]
	v_mfma_f32_16x16x32_bf16 v[36:39], v[166:169], v[206:209], v[36:39]
	v_mfma_f32_16x16x32_bf16 v[36:39], v[170:173], v[210:213], v[36:39]
	v_mfma_f32_16x16x32_bf16 v[32:35], v[178:181], v[210:213], v[32:35]
	v_mfma_f32_16x16x32_bf16 v[32:35], v[174:177], v[206:209], v[32:35]
	s_setprio 0
	s_waitcnt vmcnt(8)
	s_barrier
	ds_read_b128 v[182:185], v158 offset:16384
	ds_read_b128 v[186:189], v158 offset:17408
	ds_read_b128 v[190:193], v158 offset:18432
	ds_read_b128 v[194:197], v158 offset:19456
	ds_read_b128 v[198:201], v158 offset:20480
	ds_read_b128 v[202:205], v158 offset:21504
	ds_read_b128 v[206:209], v158 offset:22528
	ds_read_b128 v[210:213], v158 offset:23552
	s_add_u32 vcc_lo, s20, 0x404000
	s_addc_u32 vcc_hi, s21, 0
	s_add_i32 m0, s24, 0x10000
	s_nop 0
	global_load_lds_dwordx4 v138, s[20:21]
	s_add_i32 m0, s24, 0x12000
	s_nop 0
	global_load_lds_dwordx4 v142, s[20:21]
	s_add_i32 m0, s24, 0x14000
	s_nop 0
	global_load_lds_dwordx4 v138, vcc
	s_add_i32 m0, s24, 0x16000
	s_nop 0
	global_load_lds_dwordx4 v142, vcc
	s_mov_b32 m0, s24
	s_nop 0
	global_load_lds_dwordx4 v136, s[22:23]
	s_add_i32 m0, s24, 0x2000
	s_nop 0
	global_load_lds_dwordx4 v140, s[22:23]
	s_waitcnt lgkmcnt(0)
	s_setprio 1
	v_mfma_f32_16x16x32_bf16 v[92:95], v[128:131], v[182:185], v[92:95]
	v_mfma_f32_16x16x32_bf16 v[92:95], v[132:135], v[186:189], v[92:95]
	v_mfma_f32_16x16x32_bf16 v[88:91], v[162:165], v[186:189], v[88:91]
	v_mfma_f32_16x16x32_bf16 v[88:91], v[150:153], v[182:185], v[88:91]
	v_mfma_f32_16x16x32_bf16 v[28:31], v[166:169], v[182:185], v[28:31]
	v_mfma_f32_16x16x32_bf16 v[28:31], v[170:173], v[186:189], v[28:31]
	v_mfma_f32_16x16x32_bf16 v[24:27], v[178:181], v[186:189], v[24:27]
	v_mfma_f32_16x16x32_bf16 v[24:27], v[174:177], v[182:185], v[24:27]
	v_mfma_f32_16x16x32_bf16 v[84:87], v[128:131], v[190:193], v[84:87]
	v_mfma_f32_16x16x32_bf16 v[84:87], v[132:135], v[194:197], v[84:87]
	v_mfma_f32_16x16x32_bf16 v[80:83], v[162:165], v[194:197], v[80:83]
	v_mfma_f32_16x16x32_bf16 v[80:83], v[150:153], v[190:193], v[80:83]
	v_mfma_f32_16x16x32_bf16 v[20:23], v[166:169], v[190:193], v[20:23]
	v_mfma_f32_16x16x32_bf16 v[20:23], v[170:173], v[194:197], v[20:23]
	v_mfma_f32_16x16x32_bf16 v[16:19], v[178:181], v[194:197], v[16:19]
	v_mfma_f32_16x16x32_bf16 v[16:19], v[174:177], v[190:193], v[16:19]
	v_mfma_f32_16x16x32_bf16 v[76:79], v[128:131], v[198:201], v[76:79]
	v_mfma_f32_16x16x32_bf16 v[76:79], v[132:135], v[202:205], v[76:79]
	v_mfma_f32_16x16x32_bf16 v[72:75], v[162:165], v[202:205], v[72:75]
	v_mfma_f32_16x16x32_bf16 v[72:75], v[150:153], v[198:201], v[72:75]
	v_mfma_f32_16x16x32_bf16 v[12:15], v[166:169], v[198:201], v[12:15]
	v_mfma_f32_16x16x32_bf16 v[12:15], v[170:173], v[202:205], v[12:15]
	v_mfma_f32_16x16x32_bf16 v[8:11], v[178:181], v[202:205], v[8:11]
	v_mfma_f32_16x16x32_bf16 v[8:11], v[174:177], v[198:201], v[8:11]
	v_mfma_f32_16x16x32_bf16 v[60:63], v[128:131], v[206:209], v[60:63]
	v_mfma_f32_16x16x32_bf16 v[60:63], v[132:135], v[210:213], v[60:63]
	v_mfma_f32_16x16x32_bf16 v[56:59], v[162:165], v[210:213], v[56:59]
	v_mfma_f32_16x16x32_bf16 v[56:59], v[150:153], v[206:209], v[56:59]
	v_mfma_f32_16x16x32_bf16 v[4:7], v[166:169], v[206:209], v[4:7]
	v_mfma_f32_16x16x32_bf16 v[4:7], v[170:173], v[210:213], v[4:7]
	v_mfma_f32_16x16x32_bf16 v[0:3], v[178:181], v[210:213], v[0:3]
	v_mfma_f32_16x16x32_bf16 v[0:3], v[174:177], v[206:209], v[0:3]
	s_setprio 0
	s_waitcnt vmcnt(8)
	s_barrier
; #define PG8_STAGE(bufoff, gbase, voff) do { _Pragma("unroll") for (int _i = 0; _i < 2; ++_i) \
;         __builtin_amdgcn_global_load_lds((const unsigned*)((const char*)(gbase) + (voff)[_i]), (PG8_LAS unsigned*)(lds + (bufoff) + ldsw + _i * 8192), 16, 0, 0); } while (0)
; #define PG8_LDA(dst, b, h) do { _Pragma("unroll") for (int m = 0; m < 4; ++m) _Pragma("unroll") for (int k = 0; k < 2; ++k) dst[m][k] = *(const PG8_LAS bf16x8*)(lds + PG8_SA(b, h) + aoff + m * 2048 + k * 1024); } while (0)
; #define PG8_LDB(dst, b, h) do { _Pragma("unroll") for (int n = 0; n < 2; ++n) _Pragma("unroll") for (int k = 0; k < 2; ++k) dst[n][k] = *(const PG8_LAS bf16x8*)(lds + PG8_SB(b, h) + boff + n * 2048 + k * 1024); } while (0)
; #define PG8_MMA(ai, bj, At, Bt) do { __builtin_amdgcn_s_setprio(1); _Pragma("unroll") for (int m = 0; m < 4; ++m) _Pragma("unroll") for (int n = 0; n < 2; ++n) _Pragma("unroll") for (int k = 0; k < 2; ++k) \
;         acc[ai][bj][m][n] = __builtin_amdgcn_mfma_f32_16x16x32_bf16(Bt[n][k], At[m][k], acc[ai][bj][m][n], 0, 0, 0); __builtin_amdgcn_s_setprio(0); } while (0)
; #define PG8_WAIT_V(n) asm volatile("s_waitcnt vmcnt(" #n ")" ::: "memory")
; #define PG8_WAIT_L(n) asm volatile("s_waitcnt lgkmcnt(" #n ")" ::: "memory")
; #define PG8_BAR __builtin_amdgcn_s_barrier()
; #define PG8_SCHED __builtin_amdgcn_sched_barrier(0)
; template <class Epi, class Sched, bool ALIGN_EPI = false, bool SP2 = false>
; __device__ __forceinline__ void gemm_phase(PG8_LAS unsigned char* lds, const Gemm g, const Sched& S, const Epi& E) {
;     ...
;             PG8_LDB(B0, 1, 0); PG8_LDB(B1, 1, 1); PG8_SCHED; PG8_LDA(At, 1, 0); PG8_STAGE(PG8_SA(0, 1), a2 + hstep, voffA);
;             PG8_WAIT_V(8); PG8_WAIT_L(0); PG8_BAR; PG8_MMA(0, 0, At, B0); PG8_MMA(0, 1, At, B1); PG8_BAR; PG8_SCHED;
;             PG8_LDA(At, 1, 1); PG8_STAGE(PG8_SB(1, 0), b3, voffB); PG8_STAGE(PG8_SB(1, 1), b3 + hstep, voffB); PG8_STAGE(PG8_SA(1, 0), a3, voffA);
;             PG8_WAIT_V(8); PG8_WAIT_L(0); PG8_BAR; PG8_MMA(1, 0, At, B0); PG8_MMA(1, 1, At, B1); PG8_BAR; PG8_SCHED;
	ds_read_b128 v[128:131], v159
	ds_read_b128 v[132:135], v159 offset:1024
	ds_read_b128 v[150:153], v159 offset:2048
	ds_read_b128 v[162:165], v159 offset:3072
	ds_read_b128 v[166:169], v160
	ds_read_b128 v[170:173], v160 offset:1024
	ds_read_b128 v[174:177], v160 offset:2048
	ds_read_b128 v[178:181], v160 offset:3072
	ds_read_b128 v[182:185], v158 offset:32768
	ds_read_b128 v[186:189], v158 offset:33792
	ds_read_b128 v[190:193], v158 offset:34816
	ds_read_b128 v[194:197], v158 offset:35840
	ds_read_b128 v[198:201], v158 offset:36864
	ds_read_b128 v[202:205], v158 offset:37888
	ds_read_b128 v[206:209], v158 offset:38912
	ds_read_b128 v[210:213], v158 offset:39936
	s_add_u32 vcc_lo, s22, 0x404000
	s_addc_u32 vcc_hi, s23, 0
	s_add_i32 m0, s24, 0x4000
	s_nop 0
	global_load_lds_dwordx4 v136, vcc
	s_add_i32 m0, s24, 0x6000
	s_nop 0
	global_load_lds_dwordx4 v140, vcc
	s_waitcnt lgkmcnt(0)
	s_setprio 1
	v_mfma_f32_16x16x32_bf16 v[124:127], v[128:131], v[182:185], v[124:127]
	v_mfma_f32_16x16x32_bf16 v[124:127], v[132:135], v[186:189], v[124:127]
	v_mfma_f32_16x16x32_bf16 v[120:123], v[162:165], v[186:189], v[120:123]
	v_mfma_f32_16x16x32_bf16 v[120:123], v[150:153], v[182:185], v[120:123]
	v_mfma_f32_16x16x32_bf16 v[68:71], v[166:169], v[182:185], v[68:71]
	v_mfma_f32_16x16x32_bf16 v[68:71], v[170:173], v[186:189], v[68:71]
	v_mfma_f32_16x16x32_bf16 v[64:67], v[178:181], v[186:189], v[64:67]
	v_mfma_f32_16x16x32_bf16 v[64:67], v[174:177], v[182:185], v[64:67]
	v_mfma_f32_16x16x32_bf16 v[116:119], v[128:131], v[190:193], v[116:119]
	v_mfma_f32_16x16x32_bf16 v[116:119], v[132:135], v[194:197], v[116:119]
	v_mfma_f32_16x16x32_bf16 v[112:115], v[162:165], v[194:197], v[112:115]
	v_mfma_f32_16x16x32_bf16 v[112:115], v[150:153], v[190:193], v[112:115]
	v_mfma_f32_16x16x32_bf16 v[52:55], v[166:169], v[190:193], v[52:55]
	v_mfma_f32_16x16x32_bf16 v[52:55], v[170:173], v[194:197], v[52:55]
	v_mfma_f32_16x16x32_bf16 v[48:51], v[178:181], v[194:197], v[48:51]
	v_mfma_f32_16x16x32_bf16 v[48:51], v[174:177], v[190:193], v[48:51]
	v_mfma_f32_16x16x32_bf16 v[108:111], v[128:131], v[198:201], v[108:111]
	v_mfma_f32_16x16x32_bf16 v[108:111], v[132:135], v[202:205], v[108:111]
	v_mfma_f32_16x16x32_bf16 v[104:107], v[162:165], v[202:205], v[104:107]
	v_mfma_f32_16x16x32_bf16 v[104:107], v[150:153], v[198:201], v[104:107]
	v_mfma_f32_16x16x32_bf16 v[44:47], v[166:169], v[198:201], v[44:47]
	v_mfma_f32_16x16x32_bf16 v[44:47], v[170:173], v[202:205], v[44:47]
	v_mfma_f32_16x16x32_bf16 v[40:43], v[178:181], v[202:205], v[40:43]
	v_mfma_f32_16x16x32_bf16 v[40:43], v[174:177], v[198:201], v[40:43]
	v_mfma_f32_16x16x32_bf16 v[100:103], v[128:131], v[206:209], v[100:103]
	v_mfma_f32_16x16x32_bf16 v[100:103], v[132:135], v[210:213], v[100:103]
	v_mfma_f32_16x16x32_bf16 v[96:99], v[162:165], v[210:213], v[96:99]
	v_mfma_f32_16x16x32_bf16 v[96:99], v[150:153], v[206:209], v[96:99]
	v_mfma_f32_16x16x32_bf16 v[36:39], v[166:169], v[206:209], v[36:39]
	v_mfma_f32_16x16x32_bf16 v[36:39], v[170:173], v[210:213], v[36:39]
	v_mfma_f32_16x16x32_bf16 v[32:35], v[178:181], v[210:213], v[32:35]
	v_mfma_f32_16x16x32_bf16 v[32:35], v[174:177], v[206:209], v[32:35]
	s_setprio 0
	s_waitcnt vmcnt(8)
	s_barrier
	ds_read_b128 v[182:185], v158 offset:49152
	ds_read_b128 v[186:189], v158 offset:50176
	ds_read_b128 v[190:193], v158 offset:51200
	ds_read_b128 v[194:197], v158 offset:52224
	ds_read_b128 v[198:201], v158 offset:53248
	ds_read_b128 v[202:205], v158 offset:54272
	ds_read_b128 v[206:209], v158 offset:55296
	ds_read_b128 v[210:213], v158 offset:56320
	s_add_u32 s60, s20, 0x80
	s_addc_u32 s61, s21, 0
	s_add_u32 vcc_lo, s60, 0x404000
	s_addc_u32 vcc_hi, s61, 0
	s_add_i32 m0, s24, 0x18000
	s_nop 0
	global_load_lds_dwordx4 v138, s[60:61]
	s_add_i32 m0, s24, 0x1a000
	s_nop 0
	global_load_lds_dwordx4 v142, s[60:61]
	s_add_i32 m0, s24, 0x1c000
	s_nop 0
	global_load_lds_dwordx4 v138, vcc
	s_add_i32 m0, s24, 0x1e000
	s_nop 0
	global_load_lds_dwordx4 v142, vcc
	s_add_u32 s60, s22, 0x80
	s_addc_u32 s61, s23, 0
	s_add_i32 m0, s24, 0x8000
	s_nop 0
	global_load_lds_dwordx4 v136, s[60:61]
	s_add_i32 m0, s24, 0xa000
	s_nop 0
	global_load_lds_dwordx4 v140, s[60:61]
	s_waitcnt lgkmcnt(0)
	s_setprio 1
	v_mfma_f32_16x16x32_bf16 v[92:95], v[128:131], v[182:185], v[92:95]
	v_mfma_f32_16x16x32_bf16 v[92:95], v[132:135], v[186:189], v[92:95]
	v_mfma_f32_16x16x32_bf16 v[88:91], v[162:165], v[186:189], v[88:91]
	v_mfma_f32_16x16x32_bf16 v[88:91], v[150:153], v[182:185], v[88:91]
	v_mfma_f32_16x16x32_bf16 v[28:31], v[166:169], v[182:185], v[28:31]
	v_mfma_f32_16x16x32_bf16 v[28:31], v[170:173], v[186:189], v[28:31]
	v_mfma_f32_16x16x32_bf16 v[24:27], v[178:181], v[186:189], v[24:27]
	v_mfma_f32_16x16x32_bf16 v[24:27], v[174:177], v[182:185], v[24:27]
	v_mfma_f32_16x16x32_bf16 v[84:87], v[128:131], v[190:193], v[84:87]
	v_mfma_f32_16x16x32_bf16 v[84:87], v[132:135], v[194:197], v[84:87]
	v_mfma_f32_16x16x32_bf16 v[80:83], v[162:165], v[194:197], v[80:83]
	v_mfma_f32_16x16x32_bf16 v[80:83], v[150:153], v[190:193], v[80:83]
	v_mfma_f32_16x16x32_bf16 v[20:23], v[166:169], v[190:193], v[20:23]
	v_mfma_f32_16x16x32_bf16 v[20:23], v[170:173], v[194:197], v[20:23]
	v_mfma_f32_16x16x32_bf16 v[16:19], v[178:181], v[194:197], v[16:19]
	v_mfma_f32_16x16x32_bf16 v[16:19], v[174:177], v[190:193], v[16:19]
	v_mfma_f32_16x16x32_bf16 v[76:79], v[128:131], v[198:201], v[76:79]
	v_mfma_f32_16x16x32_bf16 v[76:79], v[132:135], v[202:205], v[76:79]
	v_mfma_f32_16x16x32_bf16 v[72:75], v[162:165], v[202:205], v[72:75]
	v_mfma_f32_16x16x32_bf16 v[72:75], v[150:153], v[198:201], v[72:75]
	v_mfma_f32_16x16x32_bf16 v[12:15], v[166:169], v[198:201], v[12:15]
	v_mfma_f32_16x16x32_bf16 v[12:15], v[170:173], v[202:205], v[12:15]
	v_mfma_f32_16x16x32_bf16 v[8:11], v[178:181], v[202:205], v[8:11]
	v_mfma_f32_16x16x32_bf16 v[8:11], v[174:177], v[198:201], v[8:11]
	v_mfma_f32_16x16x32_bf16 v[60:63], v[128:131], v[206:209], v[60:63]
	v_mfma_f32_16x16x32_bf16 v[60:63], v[132:135], v[210:213], v[60:63]
	v_mfma_f32_16x16x32_bf16 v[56:59], v[162:165], v[210:213], v[56:59]
	v_mfma_f32_16x16x32_bf16 v[56:59], v[150:153], v[206:209], v[56:59]
	v_mfma_f32_16x16x32_bf16 v[4:7], v[166:169], v[206:209], v[4:7]
	v_mfma_f32_16x16x32_bf16 v[4:7], v[170:173], v[210:213], v[4:7]
	v_mfma_f32_16x16x32_bf16 v[0:3], v[178:181], v[210:213], v[0:3]
	v_mfma_f32_16x16x32_bf16 v[0:3], v[174:177], v[206:209], v[0:3]
	s_setprio 0
	s_waitcnt vmcnt(8)
	s_barrier
	s_add_i32 s59, s59, 2
	s_add_u32 s18, s18, 0x100
	s_addc_u32 s19, s19, 0
	s_add_u32 s57, s57, 0x100
	s_addc_u32 s58, s58, 0
	s_cmpk_gt_u32 s59, 0xfd
	s_cbranch_scc0 .LBB0_1321
	s_branch .Lf2_exit
; #define PG8_STAGE(bufoff, gbase, voff) do { _Pragma("unroll") for (int _i = 0; _i < 2; ++_i) \
;         __builtin_amdgcn_global_load_lds((const unsigned*)((const char*)(gbase) + (voff)[_i]), (PG8_LAS unsigned*)(lds + (bufoff) + ldsw + _i * 8192), 16, 0, 0); } while (0)
; #define PG8_LDA(dst, b, h) do { _Pragma("unroll") for (int m = 0; m < 4; ++m) _Pragma("unroll") for (int k = 0; k < 2; ++k) dst[m][k] = *(const PG8_LAS bf16x8*)(lds + PG8_SA(b, h) + aoff + m * 2048 + k * 1024); } while (0)
; #define PG8_LDB(dst, b, h) do { _Pragma("unroll") for (int n = 0; n < 2; ++n) _Pragma("unroll") for (int k = 0; k < 2; ++k) dst[n][k] = *(const PG8_LAS bf16x8*)(lds + PG8_SB(b, h) + boff + n * 2048 + k * 1024); } while (0)
; #define PG8_MMA(ai, bj, At, Bt) do { __builtin_amdgcn_s_setprio(1); _Pragma("unroll") for (int m = 0; m < 4; ++m) _Pragma("unroll") for (int n = 0; n < 2; ++n) _Pragma("unroll") for (int k = 0; k < 2; ++k) \
;         acc[ai][bj][m][n] = __builtin_amdgcn_mfma_f32_16x16x32_bf16(Bt[n][k], At[m][k], acc[ai][bj][m][n], 0, 0, 0); __builtin_amdgcn_s_setprio(0); } while (0)
; #define PG8_WAIT_V(n) asm volatile("s_waitcnt vmcnt(" #n ")" ::: "memory")
; #define PG8_WAIT_L(n) asm volatile("s_waitcnt lgkmcnt(" #n ")" ::: "memory")
; #define PG8_BAR __builtin_amdgcn_s_barrier()
; #define PG8_SCHED __builtin_amdgcn_sched_barrier(0)
; template <class Epi, class Sched, bool ALIGN_EPI = false, bool SP2 = false>
; __device__ __forceinline__ void gemm_phase(PG8_LAS unsigned char* lds, const Gemm g, const Sched& S, const Epi& E) {
;     ...
;             PG8_LDB(B0, 0, 0); PG8_LDB(B1, 0, 1); PG8_SCHED; PG8_LDA(At, 0, 0); PG8_STAGE(PG8_SA(1, 1), a1 + hstep, voffA);
;             PG8_WAIT_V(8); PG8_WAIT_L(0); PG8_BAR; PG8_MMA(0, 0, At, B0); PG8_MMA(0, 1, At, B1); PG8_BAR; PG8_SCHED;
;             PG8_LDA(At, 0, 1); PG8_STAGE(PG8_SB(0, 0), b2, voffB); PG8_STAGE(PG8_SB(0, 1), b2 + hstep, voffB); PG8_STAGE(PG8_SA(0, 0), a2, voffA);
;             PG8_WAIT_V(8); PG8_WAIT_L(0); PG8_BAR; PG8_MMA(1, 0, At, B0); PG8_MMA(1, 1, At, B1); PG8_BAR; PG8_SCHED;
.Lf2_h1:
	ds_read_b128 v[128:131], v156
	ds_read_b128 v[132:135], v156 offset:1024
	ds_read_b128 v[150:153], v156 offset:2048
	ds_read_b128 v[162:165], v156 offset:3072
	ds_read_b128 v[166:169], v157
	ds_read_b128 v[170:173], v157 offset:1024
	ds_read_b128 v[174:177], v157 offset:2048
	ds_read_b128 v[178:181], v157 offset:3072
	s_add_u32 s20, s18, 0xffbfc080
	s_addc_u32 s21, s19, -1
	s_cmpk_eq_i32 s59, 0xfc
	s_cselect_b32 s23, s7, s21
	s_cselect_b32 s22, s6, s20
	s_cselect_b32 s21, s17, s58
	s_cselect_b32 s20, s16, s57
	ds_read_b128 v[182:185], v158
	ds_read_b128 v[186:189], v158 offset:1024
	ds_read_b128 v[190:193], v158 offset:2048
	ds_read_b128 v[194:197], v158 offset:3072
	ds_read_b128 v[198:201], v158 offset:4096
	ds_read_b128 v[202:205], v158 offset:5120
	ds_read_b128 v[206:209], v158 offset:6144
	ds_read_b128 v[210:213], v158 offset:7168
	s_add_i32 m0, s24, 0xc000
	s_nop 0
	global_load_lds_dwordx4 v136, s[18:19]
	s_add_i32 m0, s24, 0xe000
	s_nop 0
	global_load_lds_dwordx4 v140, s[18:19]
	s_sleep 2
	s_waitcnt lgkmcnt(0)
	s_waitcnt vmcnt(8)
	s_barrier
	s_setprio 2
	v_mfma_f32_16x16x32_bf16 v[124:127], v[128:131], v[182:185], v[124:127]
	v_mfma_f32_16x16x32_bf16 v[124:127], v[132:135], v[186:189], v[124:127]
	v_mfma_f32_16x16x32_bf16 v[120:123], v[162:165], v[186:189], v[120:123]
	v_mfma_f32_16x16x32_bf16 v[120:123], v[150:153], v[182:185], v[120:123]
	v_mfma_f32_16x16x32_bf16 v[68:71], v[166:169], v[182:185], v[68:71]
	v_mfma_f32_16x16x32_bf16 v[68:71], v[170:173], v[186:189], v[68:71]
	v_mfma_f32_16x16x32_bf16 v[64:67], v[178:181], v[186:189], v[64:67]
	v_mfma_f32_16x16x32_bf16 v[64:67], v[174:177], v[182:185], v[64:67]
	v_mfma_f32_16x16x32_bf16 v[116:119], v[128:131], v[190:193], v[116:119]
	v_mfma_f32_16x16x32_bf16 v[116:119], v[132:135], v[194:197], v[116:119]
	v_mfma_f32_16x16x32_bf16 v[112:115], v[162:165], v[194:197], v[112:115]
	v_mfma_f32_16x16x32_bf16 v[112:115], v[150:153], v[190:193], v[112:115]
	v_mfma_f32_16x16x32_bf16 v[52:55], v[166:169], v[190:193], v[52:55]
	v_mfma_f32_16x16x32_bf16 v[52:55], v[170:173], v[194:197], v[52:55]
	v_mfma_f32_16x16x32_bf16 v[48:51], v[178:181], v[194:197], v[48:51]
	v_mfma_f32_16x16x32_bf16 v[48:51], v[174:177], v[190:193], v[48:51]
	v_mfma_f32_16x16x32_bf16 v[108:111], v[128:131], v[198:201], v[108:111]
	v_mfma_f32_16x16x32_bf16 v[108:111], v[132:135], v[202:205], v[108:111]
	v_mfma_f32_16x16x32_bf16 v[104:107], v[162:165], v[202:205], v[104:107]
	v_mfma_f32_16x16x32_bf16 v[104:107], v[150:153], v[198:201], v[104:107]
	v_mfma_f32_16x16x32_bf16 v[44:47], v[166:169], v[198:201], v[44:47]
	v_mfma_f32_16x16x32_bf16 v[44:47], v[170:173], v[202:205], v[44:47]
	v_mfma_f32_16x16x32_bf16 v[40:43], v[178:181], v[202:205], v[40:43]
	v_mfma_f32_16x16x32_bf16 v[40:43], v[174:177], v[198:201], v[40:43]
	v_mfma_f32_16x16x32_bf16 v[100:103], v[128:131], v[206:209], v[100:103]
	v_mfma_f32_16x16x32_bf16 v[100:103], v[132:135], v[210:213], v[100:103]
	v_mfma_f32_16x16x32_bf16 v[96:99], v[162:165], v[210:213], v[96:99]
	v_mfma_f32_16x16x32_bf16 v[96:99], v[150:153], v[206:209], v[96:99]
	v_mfma_f32_16x16x32_bf16 v[36:39], v[166:169], v[206:209], v[36:39]
	v_mfma_f32_16x16x32_bf16 v[36:39], v[170:173], v[210:213], v[36:39]
	v_mfma_f32_16x16x32_bf16 v[32:35], v[178:181], v[210:213], v[32:35]
	v_mfma_f32_16x16x32_bf16 v[32:35], v[174:177], v[206:209], v[32:35]
	s_setprio 0
	ds_read_b128 v[182:185], v158 offset:16384
	ds_read_b128 v[186:189], v158 offset:17408
	ds_read_b128 v[190:193], v158 offset:18432
	ds_read_b128 v[194:197], v158 offset:19456
	ds_read_b128 v[198:201], v158 offset:20480
	ds_read_b128 v[202:205], v158 offset:21504
	ds_read_b128 v[206:209], v158 offset:22528
	ds_read_b128 v[210:213], v158 offset:23552
	s_add_u32 vcc_lo, s20, 0x404000
	s_addc_u32 vcc_hi, s21, 0
	s_add_i32 m0, s24, 0x10000
	s_nop 0
	global_load_lds_dwordx4 v138, s[20:21]
	s_add_i32 m0, s24, 0x12000
	s_nop 0
	global_load_lds_dwordx4 v142, s[20:21]
	s_add_i32 m0, s24, 0x14000
	s_nop 0
	global_load_lds_dwordx4 v138, vcc
	s_add_i32 m0, s24, 0x16000
	s_nop 0
	global_load_lds_dwordx4 v142, vcc
	s_mov_b32 m0, s24
	s_nop 0
	global_load_lds_dwordx4 v136, s[22:23]
	s_add_i32 m0, s24, 0x2000
	s_nop 0
	global_load_lds_dwordx4 v140, s[22:23]
	s_sleep 2
	s_waitcnt lgkmcnt(0)
	s_waitcnt vmcnt(8)
	s_barrier
; #define PG8_STAGE(bufoff, gbase, voff) do { _Pragma("unroll") for (int _i = 0; _i < 2; ++_i) \
;         __builtin_amdgcn_global_load_lds((const unsigned*)((const char*)(gbase) + (voff)[_i]), (PG8_LAS unsigned*)(lds + (bufoff) + ldsw + _i * 8192), 16, 0, 0); } while (0)
; #define PG8_LDA(dst, b, h) do { _Pragma("unroll") for (int m = 0; m < 4; ++m) _Pragma("unroll") for (int k = 0; k < 2; ++k) dst[m][k] = *(const PG8_LAS bf16x8*)(lds + PG8_SA(b, h) + aoff + m * 2048 + k * 1024); } while (0)
; #define PG8_LDB(dst, b, h) do { _Pragma("unroll") for (int n = 0; n < 2; ++n) _Pragma("unroll") for (int k = 0; k < 2; ++k) dst[n][k] = *(const PG8_LAS bf16x8*)(lds + PG8_SB(b, h) + boff + n * 2048 + k * 1024); } while (0)
; #define PG8_MMA(ai, bj, At, Bt) do { __builtin_amdgcn_s_setprio(1); _Pragma("unroll") for (int m = 0; m < 4; ++m) _Pragma("unroll") for (int n = 0; n < 2; ++n) _Pragma("unroll") for (int k = 0; k < 2; ++k) \
;         acc[ai][bj][m][n] = __builtin_amdgcn_mfma_f32_16x16x32_bf16(Bt[n][k], At[m][k], acc[ai][bj][m][n], 0, 0, 0); __builtin_amdgcn_s_setprio(0); } while (0)
; #define PG8_WAIT_V(n) asm volatile("s_waitcnt vmcnt(" #n ")" ::: "memory")
; #define PG8_WAIT_L(n) asm volatile("s_waitcnt lgkmcnt(" #n ")" ::: "memory")
; #define PG8_BAR __builtin_amdgcn_s_barrier()
; #define PG8_SCHED __builtin_amdgcn_sched_barrier(0)
; template <class Epi, class Sched, bool ALIGN_EPI = false, bool SP2 = false>
; __device__ __forceinline__ void gemm_phase(PG8_LAS unsigned char* lds, const Gemm g, const Sched& S, const Epi& E) {
;     ...
;             PG8_WAIT_V(8); PG8_WAIT_L(0); PG8_BAR; PG8_MMA(1, 0, At, B0); PG8_MMA(1, 1, At, B1); PG8_BAR; PG8_SCHED;
;             PG8_LDB(B0, 1, 0); PG8_LDB(B1, 1, 1); PG8_SCHED; PG8_LDA(At, 1, 0); PG8_STAGE(PG8_SA(0, 1), a2 + hstep, voffA);
;             PG8_WAIT_V(8); PG8_WAIT_L(0); PG8_BAR; PG8_MMA(0, 0, At, B0); PG8_MMA(0, 1, At, B1); PG8_BAR; PG8_SCHED;
	s_setprio 2
	v_mfma_f32_16x16x32_bf16 v[92:95], v[128:131], v[182:185], v[92:95]
	v_mfma_f32_16x16x32_bf16 v[92:95], v[132:135], v[186:189], v[92:95]
	v_mfma_f32_16x16x32_bf16 v[88:91], v[162:165], v[186:189], v[88:91]
	v_mfma_f32_16x16x32_bf16 v[88:91], v[150:153], v[182:185], v[88:91]
	v_mfma_f32_16x16x32_bf16 v[28:31], v[166:169], v[182:185], v[28:31]
	v_mfma_f32_16x16x32_bf16 v[28:31], v[170:173], v[186:189], v[28:31]
	v_mfma_f32_16x16x32_bf16 v[24:27], v[178:181], v[186:189], v[24:27]
	v_mfma_f32_16x16x32_bf16 v[24:27], v[174:177], v[182:185], v[24:27]
	v_mfma_f32_16x16x32_bf16 v[84:87], v[128:131], v[190:193], v[84:87]
	v_mfma_f32_16x16x32_bf16 v[84:87], v[132:135], v[194:197], v[84:87]
	v_mfma_f32_16x16x32_bf16 v[80:83], v[162:165], v[194:197], v[80:83]
	v_mfma_f32_16x16x32_bf16 v[80:83], v[150:153], v[190:193], v[80:83]
	v_mfma_f32_16x16x32_bf16 v[20:23], v[166:169], v[190:193], v[20:23]
	v_mfma_f32_16x16x32_bf16 v[20:23], v[170:173], v[194:197], v[20:23]
	v_mfma_f32_16x16x32_bf16 v[16:19], v[178:181], v[194:197], v[16:19]
	v_mfma_f32_16x16x32_bf16 v[16:19], v[174:177], v[190:193], v[16:19]
	v_mfma_f32_16x16x32_bf16 v[76:79], v[128:131], v[198:201], v[76:79]
	v_mfma_f32_16x16x32_bf16 v[76:79], v[132:135], v[202:205], v[76:79]
	v_mfma_f32_16x16x32_bf16 v[72:75], v[162:165], v[202:205], v[72:75]
	v_mfma_f32_16x16x32_bf16 v[72:75], v[150:153], v[198:201], v[72:75]
	v_mfma_f32_16x16x32_bf16 v[12:15], v[166:169], v[198:201], v[12:15]
	v_mfma_f32_16x16x32_bf16 v[12:15], v[170:173], v[202:205], v[12:15]
	v_mfma_f32_16x16x32_bf16 v[8:11], v[178:181], v[202:205], v[8:11]
	v_mfma_f32_16x16x32_bf16 v[8:11], v[174:177], v[198:201], v[8:11]
	v_mfma_f32_16x16x32_bf16 v[60:63], v[128:131], v[206:209], v[60:63]
	v_mfma_f32_16x16x32_bf16 v[60:63], v[132:135], v[210:213], v[60:63]
	v_mfma_f32_16x16x32_bf16 v[56:59], v[162:165], v[210:213], v[56:59]
	v_mfma_f32_16x16x32_bf16 v[56:59], v[150:153], v[206:209], v[56:59]
	v_mfma_f32_16x16x32_bf16 v[4:7], v[166:169], v[206:209], v[4:7]
	v_mfma_f32_16x16x32_bf16 v[4:7], v[170:173], v[210:213], v[4:7]
	v_mfma_f32_16x16x32_bf16 v[0:3], v[178:181], v[210:213], v[0:3]
	v_mfma_f32_16x16x32_bf16 v[0:3], v[174:177], v[206:209], v[0:3]
	s_setprio 0
	ds_read_b128 v[128:131], v159
	ds_read_b128 v[132:135], v159 offset:1024
	ds_read_b128 v[150:153], v159 offset:2048
	ds_read_b128 v[162:165], v159 offset:3072
	ds_read_b128 v[166:169], v160
	ds_read_b128 v[170:173], v160 offset:1024
	ds_read_b128 v[174:177], v160 offset:2048
	ds_read_b128 v[178:181], v160 offset:3072
	ds_read_b128 v[182:185], v158 offset:32768
	ds_read_b128 v[186:189], v158 offset:33792
	ds_read_b128 v[190:193], v158 offset:34816
	ds_read_b128 v[194:197], v158 offset:35840
	ds_read_b128 v[198:201], v158 offset:36864
	ds_read_b128 v[202:205], v158 offset:37888
	ds_read_b128 v[206:209], v158 offset:38912
	ds_read_b128 v[210:213], v158 offset:39936
	s_add_u32 vcc_lo, s22, 0x404000
	s_addc_u32 vcc_hi, s23, 0
	s_add_i32 m0, s24, 0x4000
	s_nop 0
	global_load_lds_dwordx4 v136, vcc
	s_add_i32 m0, s24, 0x6000
	s_nop 0
	global_load_lds_dwordx4 v140, vcc
	s_sleep 2
	s_waitcnt lgkmcnt(0)
	s_waitcnt vmcnt(8)
	s_barrier
; #define PG8_STAGE(bufoff, gbase, voff) do { _Pragma("unroll") for (int _i = 0; _i < 2; ++_i) \
;         __builtin_amdgcn_global_load_lds((const unsigned*)((const char*)(gbase) + (voff)[_i]), (PG8_LAS unsigned*)(lds + (bufoff) + ldsw + _i * 8192), 16, 0, 0); } while (0)
; #define PG8_LDA(dst, b, h) do { _Pragma("unroll") for (int m = 0; m < 4; ++m) _Pragma("unroll") for (int k = 0; k < 2; ++k) dst[m][k] = *(const PG8_LAS bf16x8*)(lds + PG8_SA(b, h) + aoff + m * 2048 + k * 1024); } while (0)
; #define PG8_MMA(ai, bj, At, Bt) do { __builtin_amdgcn_s_setprio(1); _Pragma("unroll") for (int m = 0; m < 4; ++m) _Pragma("unroll") for (int n = 0; n < 2; ++n) _Pragma("unroll") for (int k = 0; k < 2; ++k) \
;         acc[ai][bj][m][n] = __builtin_amdgcn_mfma_f32_16x16x32_bf16(Bt[n][k], At[m][k], acc[ai][bj][m][n], 0, 0, 0); __builtin_amdgcn_s_setprio(0); } while (0)
; #define PG8_WAIT_V(n) asm volatile("s_waitcnt vmcnt(" #n ")" ::: "memory")
; #define PG8_WAIT_L(n) asm volatile("s_waitcnt lgkmcnt(" #n ")" ::: "memory")
; #define PG8_BAR __builtin_amdgcn_s_barrier()
; #define PG8_SCHED __builtin_amdgcn_sched_barrier(0)
; template <class Epi, class Sched, bool ALIGN_EPI = false, bool SP2 = false>
; __device__ __forceinline__ void gemm_phase(PG8_LAS unsigned char* lds, const Gemm g, const Sched& S, const Epi& E) {
;     ...
;             PG8_WAIT_V(8); PG8_WAIT_L(0); PG8_BAR; PG8_MMA(0, 0, At, B0); PG8_MMA(0, 1, At, B1); PG8_BAR; PG8_SCHED;
;             PG8_LDA(At, 1, 1); PG8_STAGE(PG8_SB(1, 0), b3, voffB); PG8_STAGE(PG8_SB(1, 1), b3 + hstep, voffB); PG8_STAGE(PG8_SA(1, 0), a3, voffA);
;             PG8_WAIT_V(8); PG8_WAIT_L(0); PG8_BAR; PG8_MMA(1, 0, At, B0); PG8_MMA(1, 1, At, B1); PG8_BAR; PG8_SCHED;
	s_setprio 2
	v_mfma_f32_16x16x32_bf16 v[124:127], v[128:131], v[182:185], v[124:127]
	v_mfma_f32_16x16x32_bf16 v[124:127], v[132:135], v[186:189], v[124:127]
	v_mfma_f32_16x16x32_bf16 v[120:123], v[162:165], v[186:189], v[120:123]
	v_mfma_f32_16x16x32_bf16 v[120:123], v[150:153], v[182:185], v[120:123]
	v_mfma_f32_16x16x32_bf16 v[68:71], v[166:169], v[182:185], v[68:71]
	v_mfma_f32_16x16x32_bf16 v[68:71], v[170:173], v[186:189], v[68:71]
	v_mfma_f32_16x16x32_bf16 v[64:67], v[178:181], v[186:189], v[64:67]
	v_mfma_f32_16x16x32_bf16 v[64:67], v[174:177], v[182:185], v[64:67]
	v_mfma_f32_16x16x32_bf16 v[116:119], v[128:131], v[190:193], v[116:119]
	v_mfma_f32_16x16x32_bf16 v[116:119], v[132:135], v[194:197], v[116:119]
	v_mfma_f32_16x16x32_bf16 v[112:115], v[162:165], v[194:197], v[112:115]
	v_mfma_f32_16x16x32_bf16 v[112:115], v[150:153], v[190:193], v[112:115]
	v_mfma_f32_16x16x32_bf16 v[52:55], v[166:169], v[190:193], v[52:55]
	v_mfma_f32_16x16x32_bf16 v[52:55], v[170:173], v[194:197], v[52:55]
	v_mfma_f32_16x16x32_bf16 v[48:51], v[178:181], v[194:197], v[48:51]
	v_mfma_f32_16x16x32_bf16 v[48:51], v[174:177], v[190:193], v[48:51]
	v_mfma_f32_16x16x32_bf16 v[108:111], v[128:131], v[198:201], v[108:111]
	v_mfma_f32_16x16x32_bf16 v[108:111], v[132:135], v[202:205], v[108:111]
	v_mfma_f32_16x16x32_bf16 v[104:107], v[162:165], v[202:205], v[104:107]
	v_mfma_f32_16x16x32_bf16 v[104:107], v[150:153], v[198:201], v[104:107]
	v_mfma_f32_16x16x32_bf16 v[44:47], v[166:169], v[198:201], v[44:47]
	v_mfma_f32_16x16x32_bf16 v[44:47], v[170:173], v[202:205], v[44:47]
	v_mfma_f32_16x16x32_bf16 v[40:43], v[178:181], v[202:205], v[40:43]
	v_mfma_f32_16x16x32_bf16 v[40:43], v[174:177], v[198:201], v[40:43]
	v_mfma_f32_16x16x32_bf16 v[100:103], v[128:131], v[206:209], v[100:103]
	v_mfma_f32_16x16x32_bf16 v[100:103], v[132:135], v[210:213], v[100:103]
	v_mfma_f32_16x16x32_bf16 v[96:99], v[162:165], v[210:213], v[96:99]
	v_mfma_f32_16x16x32_bf16 v[96:99], v[150:153], v[206:209], v[96:99]
	v_mfma_f32_16x16x32_bf16 v[36:39], v[166:169], v[206:209], v[36:39]
	v_mfma_f32_16x16x32_bf16 v[36:39], v[170:173], v[210:213], v[36:39]
	v_mfma_f32_16x16x32_bf16 v[32:35], v[178:181], v[210:213], v[32:35]
	v_mfma_f32_16x16x32_bf16 v[32:35], v[174:177], v[206:209], v[32:35]
	s_setprio 0
	ds_read_b128 v[182:185], v158 offset:49152
	ds_read_b128 v[186:189], v158 offset:50176
	ds_read_b128 v[190:193], v158 offset:51200
	ds_read_b128 v[194:197], v158 offset:52224
	ds_read_b128 v[198:201], v158 offset:53248
	ds_read_b128 v[202:205], v158 offset:54272
	ds_read_b128 v[206:209], v158 offset:55296
	ds_read_b128 v[210:213], v158 offset:56320
	s_add_u32 s60, s20, 0x80
	s_addc_u32 s61, s21, 0
	s_add_u32 vcc_lo, s60, 0x404000
	s_addc_u32 vcc_hi, s61, 0
	s_add_i32 m0, s24, 0x18000
	s_nop 0
	global_load_lds_dwordx4 v138, s[60:61]
	s_add_i32 m0, s24, 0x1a000
	s_nop 0
	global_load_lds_dwordx4 v142, s[60:61]
	s_add_i32 m0, s24, 0x1c000
	s_nop 0
	global_load_lds_dwordx4 v138, vcc
	s_add_i32 m0, s24, 0x1e000
	s_nop 0
	global_load_lds_dwordx4 v142, vcc
	s_add_u32 s60, s22, 0x80
	s_addc_u32 s61, s23, 0
	s_add_i32 m0, s24, 0x8000
	s_nop 0
	global_load_lds_dwordx4 v136, s[60:61]
	s_add_i32 m0, s24, 0xa000
	s_nop 0
	global_load_lds_dwordx4 v140, s[60:61]
	s_sleep 2
	s_waitcnt lgkmcnt(0)
	s_waitcnt vmcnt(8)
	s_barrier
	s_setprio 2
	v_mfma_f32_16x16x32_bf16 v[92:95], v[128:131], v[182:185], v[92:95]
	v_mfma_f32_16x16x32_bf16 v[92:95], v[132:135], v[186:189], v[92:95]
	v_mfma_f32_16x16x32_bf16 v[88:91], v[162:165], v[186:189], v[88:91]
	v_mfma_f32_16x16x32_bf16 v[88:91], v[150:153], v[182:185], v[88:91]
	v_mfma_f32_16x16x32_bf16 v[28:31], v[166:169], v[182:185], v[28:31]
	v_mfma_f32_16x16x32_bf16 v[28:31], v[170:173], v[186:189], v[28:31]
	v_mfma_f32_16x16x32_bf16 v[24:27], v[178:181], v[186:189], v[24:27]
	v_mfma_f32_16x16x32_bf16 v[24:27], v[174:177], v[182:185], v[24:27]
	v_mfma_f32_16x16x32_bf16 v[84:87], v[128:131], v[190:193], v[84:87]
	v_mfma_f32_16x16x32_bf16 v[84:87], v[132:135], v[194:197], v[84:87]
	v_mfma_f32_16x16x32_bf16 v[80:83], v[162:165], v[194:197], v[80:83]
	v_mfma_f32_16x16x32_bf16 v[80:83], v[150:153], v[190:193], v[80:83]
	v_mfma_f32_16x16x32_bf16 v[20:23], v[166:169], v[190:193], v[20:23]
	v_mfma_f32_16x16x32_bf16 v[20:23], v[170:173], v[194:197], v[20:23]
	v_mfma_f32_16x16x32_bf16 v[16:19], v[178:181], v[194:197], v[16:19]
	v_mfma_f32_16x16x32_bf16 v[16:19], v[174:177], v[190:193], v[16:19]
	v_mfma_f32_16x16x32_bf16 v[76:79], v[128:131], v[198:201], v[76:79]
	v_mfma_f32_16x16x32_bf16 v[76:79], v[132:135], v[202:205], v[76:79]
	v_mfma_f32_16x16x32_bf16 v[72:75], v[162:165], v[202:205], v[72:75]
	v_mfma_f32_16x16x32_bf16 v[72:75], v[150:153], v[198:201], v[72:75]
	v_mfma_f32_16x16x32_bf16 v[12:15], v[166:169], v[198:201], v[12:15]
	v_mfma_f32_16x16x32_bf16 v[12:15], v[170:173], v[202:205], v[12:15]
	v_mfma_f32_16x16x32_bf16 v[8:11], v[178:181], v[202:205], v[8:11]
	v_mfma_f32_16x16x32_bf16 v[8:11], v[174:177], v[198:201], v[8:11]
	v_mfma_f32_16x16x32_bf16 v[60:63], v[128:131], v[206:209], v[60:63]
	v_mfma_f32_16x16x32_bf16 v[60:63], v[132:135], v[210:213], v[60:63]
	v_mfma_f32_16x16x32_bf16 v[56:59], v[162:165], v[210:213], v[56:59]
	v_mfma_f32_16x16x32_bf16 v[56:59], v[150:153], v[206:209], v[56:59]
	v_mfma_f32_16x16x32_bf16 v[4:7], v[166:169], v[206:209], v[4:7]
	v_mfma_f32_16x16x32_bf16 v[4:7], v[170:173], v[210:213], v[4:7]
	v_mfma_f32_16x16x32_bf16 v[0:3], v[178:181], v[210:213], v[0:3]
	v_mfma_f32_16x16x32_bf16 v[0:3], v[174:177], v[206:209], v[0:3]
	s_setprio 0
	s_add_i32 s59, s59, 2
	s_add_u32 s18, s18, 0x100
	s_addc_u32 s19, s19, 0
	s_add_u32 s57, s57, 0x100
	s_addc_u32 s58, s58, 0
	s_cmpk_gt_u32 s59, 0xfd
	s_cbranch_scc0 .Lf2_h1
